# lane^16/lane^32 ds_bpermute shuffles in the masked attention tiles and compressed-branch pass replaced by v_permlane16/32_swap (113 sites)
# baseline (speedup 1.0000x reference)
.LBB0_63:
	v_cmp_ge_i32_e32 vcc, s23, v171
	v_cmp_le_i32_e64 s[4:5], s23, v170
	s_and_b64 s[4:5], vcc, s[4:5]
	s_and_saveexec_b64 s[16:17], s[4:5]
	s_cbranch_execz .LBB0_65
	v_readfirstlane_b32 s4, v170
	s_cmp_lt_i32 s23, s4
	s_cbranch_scc1 .Lfoxf_lazy
	v_mov_b32_e32 v64, v157
	v_mov_b32_e32 v65, v156
	v_mov_b32_e32 v66, v151
	v_mov_b32_e32 v67, v150
	s_nop 1
	v_permlane16_swap_b32_e32 v157, v64
	v_permlane16_swap_b32_e32 v156, v65
	v_permlane16_swap_b32_e32 v151, v66
	v_permlane16_swap_b32_e32 v150, v67
	v_add_f32_e32 v157, v157, v64
	v_add_f32_e32 v156, v156, v65
	v_add_f32_e32 v151, v151, v66
	v_add_f32_e32 v150, v150, v67
	v_mov_b32_e32 v64, v157
	v_mov_b32_e32 v65, v156
	v_mov_b32_e32 v66, v151
	v_mov_b32_e32 v67, v150
	s_nop 1
	v_permlane32_swap_b32_e32 v157, v64
	v_permlane32_swap_b32_e32 v156, v65
	v_permlane32_swap_b32_e32 v151, v66
	v_permlane32_swap_b32_e32 v150, v67
	v_add_f32_e32 v157, v157, v64
	v_add_f32_e32 v156, v156, v65
	v_add_f32_e32 v151, v151, v66
	v_add_f32_e32 v150, v150, v67
	s_lshl_b32 s84, s23, 6
	v_lshl_add_u64 v[158:159], s[84:85], 2, v[146:147]
	global_load_dwordx4 v[88:91], v[158:159], off
	global_load_dwordx4 v[84:87], v[158:159], off offset:64
	s_lshl_b32 s4, s21, 14
	v_or_b32_e32 v109, s4, v178
	v_and_b32_e32 v64, 64, v200
	v_add_u32_e32 v108, v175, v176
	v_add_u32_e32 v196, v109, v176
	v_add_u32_e32 v162, v175, v177
	v_add_u32_e32 v82, 64, v64
	ds_read_b128 v[64:67], v108 offset:32768
	ds_read_b128 v[72:75], v108 offset:34816
	ds_read_b128 v[76:79], v162 offset:32768
	ds_read_b128 v[68:71], v162 offset:34816
	ds_read_b128 v[112:115], v196
	ds_read_b128 v[116:119], v196 offset:2048
	v_add_u32_e32 v194, v109, v177
	ds_read_b128 v[120:123], v194
	ds_read_b128 v[124:127], v194 offset:2048
	v_xor_b32_e32 v80, 16, v200
	v_xor_b32_e32 v81, 32, v200
	v_cmp_lt_i32_e32 vcc, v80, v82
	s_waitcnt lgkmcnt(0)
	v_mfma_f32_16x16x32_bf16 v[92:95], v[116:119], v[64:67], 0
	v_cndmask_b32_e32 v96, v200, v80, vcc
	v_cmp_lt_i32_e32 vcc, v81, v82
	v_lshlrev_b32_e32 v187, 2, v96
	v_mfma_f32_16x16x32_bf16 v[92:95], v[124:127], v[76:79], v[92:95]
	v_cndmask_b32_e32 v100, v200, v81, vcc
	v_or_b32_e32 v191, s84, v180
	v_or_b32_e32 v110, s4, v179
	v_mfma_f32_16x16x32_bf16 v[80:83], v[112:115], v[64:67], 0
	v_or_b32_e32 v219, 2, v191
	v_cmp_lt_i32_e64 s[4:5], v191, v130
	v_or_b32_e32 v216, 3, v191
	v_mfma_f32_16x16x32_bf16 v[96:99], v[120:123], v[76:79], v[80:83]
	v_or_b32_e32 v218, 16, v191
	v_lshlrev_b32_e32 v149, 2, v100
	v_or_b32_e32 v215, 17, v191
	v_cmp_gt_i32_e32 vcc, v191, v130
	v_or_b32_e32 v217, 18, v191
	v_or_b32_e32 v214, 19, v191
	v_add_u32_e32 v101, v109, v181
	v_add_u32_e32 v102, v109, v182
	s_waitcnt vmcnt(0)
	ds_read2st64_b64 v[208:211], v101 offset0:16 offset1:20
	ds_read2st64_b64 v[80:83], v102 offset0:16 offset1:20
	v_add_u32_e32 v105, v110, v182
	v_add_u32_e32 v104, v110, v181
	v_or_b32_e32 v192, 32, v191
	v_or_b32_e32 v190, 33, v191
	v_or_b32_e32 v193, 48, v191
	v_or_b32_e32 v197, 50, v191
	v_sub_f32_e32 v103, v131, v89
	v_sub_f32_e32 v106, v131, v90
	v_sub_f32_e32 v160, v131, v85
	v_add_f32_e32 v97, v103, v97
	v_sub_f32_e32 v107, v131, v91
	v_sub_f32_e32 v161, v131, v86
	v_add_f32_e32 v98, v106, v98
	v_add_f32_e32 v93, v160, v93
	v_cndmask_b32_e64 v160, v204, v97, s[4:5]
	v_cmp_le_i32_e64 s[4:5], v219, v130
	v_sub_f32_e32 v100, v131, v88
	v_sub_f32_e32 v111, v131, v84
	v_sub_f32_e32 v163, v131, v87
	v_add_f32_e32 v99, v107, v99
	v_add_f32_e32 v94, v161, v94
	v_cndmask_b32_e64 v161, v204, v98, s[4:5]
	v_cmp_le_i32_e64 s[4:5], v216, v130
	v_add_f32_e32 v96, v100, v96
	v_add_f32_e32 v92, v111, v92
	v_add_f32_e32 v95, v163, v95
	v_cndmask_b32_e64 v163, v204, v99, s[4:5]
	v_cmp_le_i32_e64 s[4:5], v218, v130
	v_cndmask_b32_e32 v111, v96, v204, vcc
	v_max3_f32 v96, v111, s75, v160
	v_cndmask_b32_e64 v92, v204, v92, s[4:5]
	v_cmp_le_i32_e64 s[4:5], v215, v130
	v_max3_f32 v96, v96, v161, v163
	v_sub_f32_e32 v234, v168, v88
	v_cndmask_b32_e64 v93, v204, v93, s[4:5]
	v_cmp_le_i32_e64 s[4:5], v217, v130
	v_max3_f32 v96, v96, v92, v93
	v_sub_f32_e32 v235, v168, v89
	v_cndmask_b32_e64 v94, v204, v94, s[4:5]
	v_cmp_le_i32_e64 s[4:5], v214, v130
	v_sub_f32_e32 v236, v168, v90
	v_sub_f32_e32 v237, v168, v91
	v_cndmask_b32_e64 v95, v204, v95, s[4:5]
	v_max3_f32 v106, v96, v94, v95
	v_mov_b32_e32 v107, v106
	s_nop 1
	v_permlane16_swap_b32_e32 v107, v106
	ds_read_b64 v[100:101], v101 offset:12288
	ds_read_b64 v[102:103], v102 offset:12288
	ds_read_b64 v[96:97], v104 offset:8192
	ds_read_b64 v[98:99], v105 offset:8192
	s_waitcnt lgkmcnt(5)
	v_mov_b32_e32 v105, v209
	v_sub_f32_e32 v242, v169, v88
	v_sub_f32_e32 v243, v169, v89
	s_waitcnt lgkmcnt(4)
	v_max_f32_e32 v107, v107, v107
	v_max_f32_e32 v164, v106, v107
	v_mov_b32_e32 v165, v164
	s_nop 1
	v_permlane32_swap_b32_e32 v165, v164
	v_mov_b32_e32 v106, v80
	v_mov_b32_e32 v107, v81
	v_mov_b32_e32 v80, v210
	v_mov_b32_e32 v81, v211
	s_waitcnt lgkmcnt(0)
	v_max3_f32 v209, v186, v164, v165
	v_sub_f32_e32 v92, v92, v209
	v_exp_f32_e32 v229, v92
	v_sub_f32_e32 v92, v93, v209
	v_mfma_f32_16x16x32_bf16 v[210:213], v[112:115], v[72:75], 0
	v_sub_f32_e32 v160, v160, v209
	v_exp_f32_e32 v231, v92
	v_sub_f32_e32 v92, v94, v209
	v_sub_f32_e32 v161, v161, v209
	v_exp_f32_e32 v165, v160
	v_sub_f32_e32 v160, v163, v209
	v_exp_f32_e32 v93, v92
	v_sub_f32_e32 v92, v95, v209
	v_exp_f32_e32 v225, v161
	v_exp_f32_e32 v227, v160
	v_exp_f32_e32 v95, v92
	v_sub_f32_e32 v92, v155, v88
	v_sub_f32_e32 v94, v155, v89
	v_sub_f32_e32 v160, v155, v90
	v_sub_f32_e32 v161, v155, v91
	v_sub_f32_e32 v244, v169, v90
	v_sub_f32_e32 v245, v169, v91
	v_mfma_f32_16x16x32_bf16 v[88:91], v[116:119], v[72:75], 0
	v_sub_f32_e32 v164, v186, v209
	v_mov_b32_e32 v104, v208
	v_exp_f32_e32 v208, v164
	v_mfma_f32_16x16x32_bf16 v[220:223], v[120:123], v[68:71], v[210:213]
	v_sub_f32_e32 v163, v155, v84
	v_sub_f32_e32 v164, v155, v85
	v_sub_f32_e32 v188, v155, v86
	v_sub_f32_e32 v189, v155, v87
	v_sub_f32_e32 v238, v168, v84
	v_sub_f32_e32 v239, v168, v85
	v_sub_f32_e32 v240, v168, v86
	v_sub_f32_e32 v241, v168, v87
	v_sub_f32_e32 v246, v169, v84
	v_sub_f32_e32 v247, v169, v85
	v_sub_f32_e32 v248, v169, v86
	v_sub_f32_e32 v249, v169, v87
	v_mfma_f32_16x16x32_bf16 v[84:87], v[124:127], v[68:71], v[88:91]
	v_cmp_le_i32_e64 s[4:5], v191, v172
	v_add_u32_e32 v186, v109, v183
	v_add_u32_e32 v210, v109, v184
	v_add_f32_e32 v88, v92, v220
	v_cndmask_b32_e64 v88, v204, v88, s[4:5]
	v_add_f32_e32 v89, v94, v221
	v_cmp_lt_i32_e64 s[4:5], v191, v172
	v_add_f32_e32 v91, v160, v222
	v_add_f32_e32 v92, v161, v223
	v_cndmask_b32_e64 v90, v204, v89, s[4:5]
	v_cmp_le_i32_e64 s[4:5], v219, v172
	v_add_f32_e32 v84, v163, v84
	v_cndmask_b32_e32 v94, v84, v204, vcc
	v_cndmask_b32_e64 v91, v204, v91, s[4:5]
	v_cmp_le_i32_e64 s[4:5], v216, v172
	v_add_f32_e32 v84, v164, v85
	v_max3_f32 v89, v88, s75, v90
	v_cndmask_b32_e64 v92, v204, v92, s[4:5]
	v_cmp_le_i32_e64 s[4:5], v215, v172
	v_add_f32_e32 v85, v188, v86
	v_max3_f32 v89, v89, v91, v92
	v_cndmask_b32_e64 v109, v204, v84, s[4:5]
	v_cmp_le_i32_e64 s[4:5], v217, v172
	v_max3_f32 v84, v89, v94, v109
	v_sub_f32_e32 v111, v111, v209
	v_cndmask_b32_e64 v160, v204, v85, s[4:5]
	v_add_f32_e32 v85, v189, v87
	v_cmp_le_i32_e64 s[4:5], v214, v172
	v_exp_f32_e32 v111, v111
	v_add_u32_e32 v212, v110, v183
	v_cndmask_b32_e64 v161, v204, v85, s[4:5]
	v_max3_f32 v84, v84, v160, v161
	v_mov_b32_e32 v85, v84
	s_nop 1
	v_permlane16_swap_b32_e32 v85, v84
	v_add_u32_e32 v213, v110, v184
	v_pk_mul_f32 v[62:63], v[62:63], v[208:209] op_sel_hi:[1,0]
	v_pk_mul_f32 v[60:61], v[60:61], v[208:209] op_sel_hi:[1,0]
	v_pk_mul_f32 v[58:59], v[58:59], v[208:209] op_sel_hi:[1,0]
	s_waitcnt lgkmcnt(0)
	v_max_f32_e32 v85, v85, v85
	v_max_f32_e32 v85, v84, v85
	v_mov_b32_e32 v86, v85
	s_nop 1
	v_permlane32_swap_b32_e32 v86, v85
	v_pk_mul_f32 v[56:57], v[56:57], v[208:209] op_sel_hi:[1,0]
	v_pk_mul_f32 v[54:55], v[54:55], v[208:209] op_sel_hi:[1,0]
	v_pk_mul_f32 v[52:53], v[52:53], v[208:209] op_sel_hi:[1,0]
	v_pk_mul_f32 v[50:51], v[50:51], v[208:209] op_sel_hi:[1,0]
	s_waitcnt lgkmcnt(0)
	v_max3_f32 v195, v185, v85, v86
	v_sub_f32_e32 v85, v88, v195
	v_exp_f32_e32 v110, v85
	v_sub_f32_e32 v90, v90, v195
	v_exp_f32_e32 v164, v90
	v_sub_f32_e32 v90, v91, v195
	v_exp_f32_e32 v224, v90
	v_sub_f32_e32 v90, v92, v195
	v_exp_f32_e32 v226, v90
	v_sub_f32_e32 v90, v94, v195
	v_pk_mul_f32 v[48:49], v[48:49], v[208:209] op_sel_hi:[1,0]
	v_cvt_pk_bf16_f32 v84, v111, v165
	v_pk_add_f32 v[88:89], v[110:111], 0 op_sel_hi:[1,0]
	v_exp_f32_e32 v228, v90
	v_sub_f32_e32 v90, v109, v195
	v_cvt_pk_bf16_f32 v85, v225, v227
	v_cvt_pk_bf16_f32 v86, v229, v231
	v_cvt_pk_bf16_f32 v87, v93, v95
	v_pk_add_f32 v[88:89], v[164:165], v[88:89]
	v_mfma_f32_16x16x32_bf16 v[60:63], v[104:107], v[84:87], v[60:63]
	v_exp_f32_e32 v230, v90
	v_sub_f32_e32 v90, v160, v195
	v_pk_add_f32 v[88:89], v[224:225], v[88:89]
	v_mfma_f32_16x16x32_bf16 v[56:59], v[80:83], v[84:87], v[56:59]
	v_exp_f32_e32 v92, v90
	v_pk_add_f32 v[88:89], v[226:227], v[88:89]
	v_sub_f32_e32 v90, v161, v195
	v_mfma_f32_16x16x32_bf16 v[52:55], v[100:103], v[84:87], v[52:55]
	v_add_f32_e64 v88, v228, v88
	v_add_f32_e64 v89, v229, v89
	v_exp_f32_e32 v94, v90
	v_cvt_pk_bf16_f32 v220, v110, v164
	v_mfma_f32_16x16x32_bf16 v[48:51], v[96:99], v[84:87], v[48:51]
	v_sub_f32_e32 v84, v185, v195
	v_exp_f32_e32 v160, v84
	ds_read_b128 v[84:87], v108 offset:36864
	v_pk_add_f32 v[110:111], v[230:231], v[88:89]
	v_cvt_pk_bf16_f32 v223, v92, v94
	ds_read_b128 v[88:91], v108 offset:38912
	v_pk_add_f32 v[92:93], v[92:93], v[110:111]
	ds_read_b128 v[108:111], v162 offset:36864
	v_cvt_pk_bf16_f32 v221, v224, v226
	s_waitcnt lgkmcnt(2)
	v_mfma_f32_16x16x32_bf16 v[224:227], v[112:115], v[84:87], 0
	v_add_f32_e64 v164, v94, v92
	v_add_f32_e64 v165, v95, v93
	v_mov_b32_e32 v233, v165
	s_nop 1
	v_permlane16_swap_b32_e32 v233, v165
	v_mov_b32_e32 v232, v164
	s_nop 1
	v_permlane16_swap_b32_e32 v232, v164
	v_cvt_pk_bf16_f32 v222, v228, v230
	v_mfma_f32_16x16x32_bf16 v[228:231], v[116:119], v[84:87], 0
	ds_read_b128 v[92:95], v162 offset:38912
	v_cmp_le_i32_e64 s[4:5], v191, v173
	s_waitcnt lgkmcnt(1)
	v_pk_add_f32 v[162:163], v[164:165], v[232:233]
	v_mfma_f32_16x16x32_bf16 v[224:227], v[120:123], v[108:111], v[224:227]
	v_mov_b32_e32 v161, v208
	v_pk_mul_f32 v[46:47], v[46:47], v[160:161] op_sel_hi:[1,0]
	v_pk_mul_f32 v[44:45], v[44:45], v[160:161] op_sel_hi:[1,0]
	v_mfma_f32_16x16x32_bf16 v[228:231], v[124:127], v[108:111], v[228:231]
	v_mul_f32_e64 v38, v38, v160
	v_mul_f32_e64 v39, v39, v160
	s_nop 1
	v_add_f32_e32 v164, v234, v224
	v_cndmask_b32_e64 v185, v204, v164, s[4:5]
	v_add_f32_e32 v164, v235, v225
	v_cmp_lt_i32_e64 s[4:5], v191, v173
	v_add_f32_e32 v165, v236, v226
	v_mfma_f32_16x16x32_bf16 v[112:115], v[112:115], v[88:91], 0
	v_cndmask_b32_e64 v224, v204, v164, s[4:5]
	v_cmp_le_i32_e64 s[4:5], v219, v173
	v_max3_f32 v164, v185, s75, v224
	v_mfma_f32_16x16x32_bf16 v[116:119], v[116:119], v[88:91], 0
	v_cndmask_b32_e64 v225, v204, v165, s[4:5]
	v_add_f32_e32 v165, v237, v227
	v_cmp_le_i32_e64 s[4:5], v216, v173
	s_waitcnt lgkmcnt(0)
	v_mfma_f32_16x16x32_bf16 v[112:115], v[120:123], v[92:95], v[112:115]
	v_mul_f32_e64 v36, v36, v160
	v_mul_f32_e64 v37, v37, v160
	v_cndmask_b32_e64 v226, v204, v165, s[4:5]
	v_add_f32_e32 v165, v238, v228
	v_cmp_le_i32_e64 s[4:5], v218, v173
	v_max3_f32 v164, v164, v225, v226
	v_pk_mul_f32 v[34:35], v[34:35], v[160:161] op_sel_hi:[1,0]
	v_cndmask_b32_e64 v228, v204, v165, s[4:5]
	v_add_f32_e32 v165, v239, v229
	v_cmp_le_i32_e64 s[4:5], v215, v173
	v_pk_mul_f32 v[32:33], v[32:33], v[160:161] op_sel_hi:[1,0]
	v_pk_mul_f32 v[30:31], v[30:31], v[160:161] op_sel_hi:[1,0]
	v_cndmask_b32_e64 v232, v204, v165, s[4:5]
	v_add_f32_e32 v165, v240, v230
	v_cmp_le_i32_e64 s[4:5], v217, v173
	v_max3_f32 v164, v164, v228, v232
	v_pk_mul_f32 v[28:29], v[28:29], v[160:161] op_sel_hi:[1,0]
	v_cndmask_b32_e64 v230, v204, v165, s[4:5]
	v_add_f32_e32 v165, v241, v231
	v_cmp_le_i32_e64 s[4:5], v214, v173
	v_mfma_f32_16x16x32_bf16 v[116:119], v[124:127], v[92:95], v[116:119]
	v_add_f32_e32 v112, v242, v112
	v_cndmask_b32_e64 v235, v204, v165, s[4:5]
	v_max3_f32 v164, v164, v230, v235
	v_mov_b32_e32 v211, v164
	s_nop 1
	v_permlane16_swap_b32_e32 v211, v164
	v_cmp_le_i32_e64 s[4:5], v191, v174
	v_mfma_f32_16x16x32_bf16 v[44:47], v[104:107], v[220:223], v[44:47]
	v_or_b32_e32 v189, 34, v191
	v_cndmask_b32_e64 v123, v204, v112, s[4:5]
	s_waitcnt lgkmcnt(0)
	v_max_f32_e32 v211, v211, v211
	v_max_f32_e32 v211, v164, v211
	v_mov_b32_e32 v227, v211
	s_nop 1
	v_permlane32_swap_b32_e32 v227, v211
	v_mfma_f32_16x16x32_bf16 v[36:39], v[80:83], v[220:223], v[36:39]
	v_add_f32_e32 v112, v243, v113
	v_cmp_lt_i32_e64 s[4:5], v191, v174
	v_add_f32_e32 v113, v244, v114
	s_waitcnt lgkmcnt(0)
	v_max3_f32 v211, v167, v211, v227
	v_sub_f32_e32 v185, v185, v211
	v_mfma_f32_16x16x32_bf16 v[32:35], v[100:103], v[220:223], v[32:35]
	v_cndmask_b32_e64 v124, v204, v112, s[4:5]
	v_cmp_le_i32_e64 s[4:5], v219, v174
	v_sub_f32_e32 v167, v167, v211
	v_mfma_f32_16x16x32_bf16 v[28:31], v[96:99], v[220:223], v[28:31]
	v_exp_f32_e32 v221, v185
	v_sub_f32_e32 v185, v224, v211
	v_exp_f32_e32 v223, v185
	v_sub_f32_e32 v185, v225, v211
	v_exp_f32_e32 v225, v185
	v_sub_f32_e32 v185, v226, v211
	v_cndmask_b32_e64 v125, v204, v113, s[4:5]
	v_add_f32_e32 v113, v245, v115
	v_cmp_le_i32_e64 s[4:5], v216, v174
	v_exp_f32_e32 v227, v185
	v_sub_f32_e32 v185, v228, v211
	v_cndmask_b32_e64 v126, v204, v113, s[4:5]
	v_add_f32_e32 v113, v246, v116
	v_cmp_le_i32_e64 s[4:5], v218, v174
	v_exp_f32_e32 v229, v185
	v_sub_f32_e32 v185, v232, v211
	v_exp_f32_e32 v234, v167
	v_sub_f32_e32 v167, v235, v211
	v_cndmask_b32_e64 v127, v204, v113, s[4:5]
	v_add_f32_e32 v113, v247, v117
	v_cmp_le_i32_e64 s[4:5], v215, v174
	v_exp_f32_e32 v231, v185
	v_sub_f32_e32 v185, v230, v211
	v_exp_f32_e32 v237, v167
	v_max3_f32 v112, v123, s75, v124
	v_cndmask_b32_e64 v167, v204, v113, s[4:5]
	v_add_f32_e32 v113, v248, v118
	v_cmp_le_i32_e64 s[4:5], v217, v174
	v_exp_f32_e32 v233, v185
	v_max3_f32 v112, v112, v125, v126
	v_cndmask_b32_e64 v185, v204, v113, s[4:5]
	v_add_f32_e32 v113, v249, v119
	v_cmp_le_i32_e64 s[4:5], v214, v174
	v_max3_f32 v112, v112, v127, v167
	v_pk_mul_f32 v[42:43], v[42:43], v[234:235] op_sel_hi:[1,0]
	v_cndmask_b32_e64 v215, v204, v113, s[4:5]
	v_max3_f32 v116, v112, v185, v215
	v_mov_b32_e32 v117, v116
	s_nop 1
	v_permlane16_swap_b32_e32 v117, v116
	global_load_dwordx4 v[112:115], v[158:159], off offset:128
	v_pk_mul_f32 v[40:41], v[40:41], v[234:235] op_sel_hi:[1,0]
	v_pk_mul_f32 v[26:27], v[26:27], v[234:235] op_sel_hi:[1,0]
	v_pk_mul_f32 v[24:25], v[24:25], v[234:235] op_sel_hi:[1,0]
	s_waitcnt lgkmcnt(0)
	v_max_f32_e32 v117, v117, v117
	v_max_f32_e32 v116, v116, v117
	v_mov_b32_e32 v117, v116
	s_nop 1
	v_permlane32_swap_b32_e32 v117, v116
	v_pk_mul_f32 v[22:23], v[22:23], v[234:235] op_sel_hi:[1,0]
	v_pk_mul_f32 v[20:21], v[20:21], v[234:235] op_sel_hi:[1,0]
	v_pk_mul_f32 v[18:19], v[18:19], v[234:235] op_sel_hi:[1,0]
	v_pk_mul_f32 v[16:17], v[16:17], v[234:235] op_sel_hi:[1,0]
	s_waitcnt lgkmcnt(0)
	v_max3_f32 v214, v166, v116, v117
	v_sub_f32_e32 v116, v123, v214
	v_exp_f32_e32 v220, v116
	v_sub_f32_e32 v116, v124, v214
	v_exp_f32_e32 v222, v116
	global_load_dwordx4 v[116:119], v[158:159], off offset:192
	v_sub_f32_e32 v123, v125, v214
	v_exp_f32_e32 v224, v123
	v_sub_f32_e32 v126, v126, v214
	v_exp_f32_e32 v226, v126
	v_sub_f32_e32 v126, v127, v214
	v_cvt_pk_bf16_f32 v120, v221, v223
	v_pk_add_f32 v[124:125], v[220:221], 0 op_sel_hi:[1,0]
	v_exp_f32_e32 v228, v126
	v_sub_f32_e32 v126, v167, v214
	v_cvt_pk_bf16_f32 v121, v225, v227
	v_cvt_pk_bf16_f32 v122, v229, v231
	v_cvt_pk_bf16_f32 v123, v233, v237
	v_pk_add_f32 v[124:125], v[222:223], v[124:125]
	v_mfma_f32_16x16x32_bf16 v[40:43], v[104:107], v[120:123], v[40:43]
	v_exp_f32_e32 v230, v126
	v_pk_add_f32 v[124:125], v[224:225], v[124:125]
	v_mov_b32_e32 v159, v234
	v_mfma_f32_16x16x32_bf16 v[24:27], v[80:83], v[120:123], v[24:27]
	v_add_f32_e64 v124, v226, v124
	v_add_f32_e64 v125, v227, v125
	v_cvt_pk_bf16_f32 v126, v228, v230
	v_cmp_le_i32_e64 s[4:5], v192, v130
	v_mfma_f32_16x16x32_bf16 v[20:23], v[100:103], v[120:123], v[20:23]
	v_add_f32_e64 v124, v228, v124
	v_add_f32_e64 v125, v229, v125
	v_or_b32_e32 v188, 35, v191
	v_pk_add_f32 v[216:217], v[230:231], v[124:125]
	v_mfma_f32_16x16x32_bf16 v[16:19], v[96:99], v[120:123], v[16:19]
	v_sub_f32_e32 v120, v166, v214
	v_exp_f32_e32 v158, v120
	v_sub_f32_e32 v124, v185, v214
	v_exp_f32_e32 v232, v124
	v_sub_f32_e32 v124, v215, v214
	v_pk_mul_f32 v[14:15], v[14:15], v[158:159] op_sel_hi:[1,0]
	v_pk_mul_f32 v[12:13], v[12:13], v[158:159] op_sel_hi:[1,0]
	v_exp_f32_e32 v236, v124
	v_cvt_pk_bf16_f32 v124, v220, v222
	v_cvt_pk_bf16_f32 v125, v224, v226
	v_cvt_pk_bf16_f32 v127, v232, v236
	v_pk_mul_f32 v[2:3], v[2:3], v[158:159] op_sel_hi:[1,0]
	v_mfma_f32_16x16x32_bf16 v[12:15], v[104:107], v[124:127], v[12:15]
	ds_read_b128 v[104:107], v196 offset:4096
	ds_read_b128 v[120:123], v196 offset:6144
	v_pk_mul_f32 v[0:1], v[0:1], v[158:159] op_sel_hi:[1,0]
	v_pk_mul_f32 v[10:11], v[10:11], v[158:159] op_sel_hi:[1,0]
	v_pk_mul_f32 v[8:9], v[8:9], v[158:159] op_sel_hi:[1,0]
	v_mfma_f32_16x16x32_bf16 v[0:3], v[100:103], v[124:127], v[0:3]
	ds_read_b128 v[100:103], v194 offset:4096
	v_pk_mul_f32 v[6:7], v[6:7], v[158:159] op_sel_hi:[1,0]
	v_pk_mul_f32 v[4:5], v[4:5], v[158:159] op_sel_hi:[1,0]
	v_mfma_f32_16x16x32_bf16 v[8:11], v[80:83], v[124:127], v[8:11]
	v_or_b32_e32 v208, 49, v191
	v_pk_add_f32 v[166:167], v[232:233], v[216:217]
	v_mov_b32_e32 v165, v163
	s_nop 1
	v_permlane32_swap_b32_e32 v165, v163
	v_mfma_f32_16x16x32_bf16 v[4:7], v[96:99], v[124:127], v[4:7]
	ds_read_b128 v[124:127], v194 offset:6144
	v_pk_add_f32 v[166:167], v[236:237], v[166:167]
	v_mov_b32_e32 v164, v162
	s_nop 1
	v_permlane32_swap_b32_e32 v164, v162
	s_waitcnt lgkmcnt(3)
	v_mfma_f32_16x16x32_bf16 v[80:83], v[104:107], v[64:67], 0
	v_mov_b32_e32 v217, v167
	s_nop 1
	v_permlane16_swap_b32_e32 v217, v167
	v_mov_b32_e32 v216, v166
	s_nop 1
	v_permlane16_swap_b32_e32 v216, v166
	v_or_b32_e32 v191, 51, v191
	s_waitcnt lgkmcnt(2)
	v_mfma_f32_16x16x32_bf16 v[96:99], v[120:123], v[64:67], 0
	s_waitcnt lgkmcnt(0)
	v_pk_add_f32 v[162:163], v[162:163], v[164:165]
	s_waitcnt lgkmcnt(0)
	v_pk_add_f32 v[164:165], v[166:167], v[216:217]
	v_mfma_f32_16x16x32_bf16 v[80:83], v[100:103], v[76:79], v[80:83]
	ds_read2st64_b64 v[64:67], v186 offset0:16 offset1:20
	ds_read2st64_b64 v[216:219], v210 offset0:16 offset1:20
	ds_bpermute_b32 v167, v149, v165
	ds_bpermute_b32 v166, v149, v164
	v_mfma_f32_16x16x32_bf16 v[76:79], v[124:127], v[76:79], v[96:99]
	s_waitcnt vmcnt(1)
	s_nop 1
	v_sub_f32_e32 v96, v131, v112
	v_add_f32_e32 v80, v96, v80
	v_cndmask_b32_e64 v185, v204, v80, s[4:5]
	v_sub_f32_e32 v80, v131, v113
	v_add_f32_e32 v80, v80, v81
	v_cmp_le_i32_e64 s[4:5], v190, v130
	v_sub_f32_e32 v81, v131, v114
	v_add_f32_e32 v81, v81, v82
	v_cndmask_b32_e64 v194, v204, v80, s[4:5]
	v_cmp_le_i32_e64 s[4:5], v189, v130
	v_max3_f32 v80, v185, s75, v194
	s_waitcnt lgkmcnt(3)
	v_mov_b32_e32 v96, v66
	v_cndmask_b32_e64 v196, v204, v81, s[4:5]
	v_sub_f32_e32 v81, v131, v115
	v_add_f32_e32 v81, v81, v83
	v_cmp_le_i32_e64 s[4:5], v188, v130
	v_mov_b32_e32 v97, v67
	s_waitcnt lgkmcnt(2)
	v_mov_b32_e32 v67, v217
	v_cndmask_b32_e64 v215, v204, v81, s[4:5]
	s_waitcnt vmcnt(0)
	v_sub_f32_e32 v81, v131, v116
	v_add_f32_e32 v76, v81, v76
	v_cmp_le_i32_e64 s[4:5], v193, v130
	v_max3_f32 v80, v80, v196, v215
	s_nop 0
	v_cndmask_b32_e64 v220, v204, v76, s[4:5]
	v_sub_f32_e32 v76, v131, v117
	v_add_f32_e32 v76, v76, v77
	v_cmp_le_i32_e64 s[4:5], v208, v130
	v_sub_f32_e32 v77, v131, v118
	v_add_f32_e32 v77, v77, v78
	v_cndmask_b32_e64 v222, v204, v76, s[4:5]
	v_cmp_le_i32_e64 s[4:5], v197, v130
	v_max3_f32 v76, v80, v220, v222
	s_nop 0
	v_cndmask_b32_e64 v224, v204, v77, s[4:5]
	v_sub_f32_e32 v77, v131, v119
	v_add_f32_e32 v77, v77, v79
	v_cmp_le_i32_e64 s[4:5], v191, v130
	s_nop 1
	v_cndmask_b32_e64 v226, v204, v77, s[4:5]
	v_max3_f32 v98, v76, v224, v226
	v_mov_b32_e32 v99, v98
	s_nop 1
	v_permlane16_swap_b32_e32 v99, v98
	ds_read_b64 v[80:81], v186 offset:12288
	ds_read_b64 v[82:83], v210 offset:12288
	ds_read_b64 v[76:77], v212 offset:8192
	ds_read_b64 v[78:79], v213 offset:8192
	v_cmp_le_i32_e64 s[4:5], v192, v172
	s_waitcnt lgkmcnt(4)
	v_max_f32_e32 v66, v99, v99
	v_max_f32_e32 v186, v98, v66
	v_mov_b32_e32 v98, v218
	v_mov_b32_e32 v99, v219
	v_mov_b32_e32 v66, v216
	v_mfma_f32_16x16x32_bf16 v[216:219], v[104:107], v[72:75], 0
	v_mov_b32_e32 v210, v186
	s_nop 1
	v_permlane32_swap_b32_e32 v210, v186
	s_waitcnt lgkmcnt(0)
	v_max3_f32 v186, v209, v186, v210
	v_mfma_f32_16x16x32_bf16 v[72:75], v[120:123], v[72:75], 0
	v_sub_f32_e32 v185, v185, v186
	v_exp_f32_e32 v213, v185
	v_sub_f32_e32 v185, v194, v186
	v_mfma_f32_16x16x32_bf16 v[216:219], v[100:103], v[68:71], v[216:219]
	v_exp_f32_e32 v221, v185
	v_sub_f32_e32 v185, v196, v186
	v_exp_f32_e32 v223, v185
	v_mfma_f32_16x16x32_bf16 v[68:71], v[124:127], v[68:71], v[72:75]
	v_sub_f32_e32 v185, v215, v186
	v_exp_f32_e32 v225, v185
	v_sub_f32_e32 v185, v220, v186
	v_sub_f32_e32 v72, v155, v112
	v_add_f32_e32 v72, v72, v216
	v_sub_f32_e32 v73, v155, v113
	v_cndmask_b32_e64 v72, v204, v72, s[4:5]
	v_add_f32_e32 v73, v73, v217
	v_cmp_le_i32_e64 s[4:5], v190, v172
	v_sub_f32_e32 v75, v155, v114
	v_add_f32_e32 v75, v75, v218
	v_cndmask_b32_e64 v73, v204, v73, s[4:5]
	v_cmp_le_i32_e64 s[4:5], v189, v172
	v_max3_f32 v74, v72, s75, v73
	v_exp_f32_e32 v227, v185
	v_cndmask_b32_e64 v194, v204, v75, s[4:5]
	v_sub_f32_e32 v75, v155, v115
	v_add_f32_e32 v75, v75, v219
	v_cmp_le_i32_e64 s[4:5], v188, v172
	v_sub_f32_e32 v185, v222, v186
	v_sub_f32_e32 v209, v209, v186
	v_cndmask_b32_e64 v196, v204, v75, s[4:5]
	v_sub_f32_e32 v75, v155, v116
	v_add_f32_e32 v68, v75, v68
	v_cmp_le_i32_e64 s[4:5], v193, v172
	v_sub_f32_e32 v75, v155, v117
	v_add_f32_e32 v69, v75, v69
	v_cndmask_b32_e64 v68, v204, v68, s[4:5]
	v_cmp_le_i32_e64 s[4:5], v208, v172
	v_max3_f32 v74, v74, v194, v196
	v_exp_f32_e32 v75, v185
	v_cndmask_b32_e64 v210, v204, v69, s[4:5]
	v_max3_f32 v69, v74, v68, v210
	v_sub_f32_e32 v74, v155, v118
	v_add_f32_e32 v70, v74, v70
	v_cmp_le_i32_e64 s[4:5], v197, v172
	s_nop 1
	v_cndmask_b32_e64 v215, v204, v70, s[4:5]
	v_sub_f32_e32 v70, v155, v119
	v_add_f32_e32 v70, v70, v71
	v_cmp_le_i32_e64 s[4:5], v191, v172
	v_sub_f32_e32 v71, v224, v186
	v_exp_f32_e32 v229, v71
	v_cndmask_b32_e64 v218, v204, v70, s[4:5]
	v_max3_f32 v69, v69, v215, v218
	v_mov_b32_e32 v70, v69
	s_nop 1
	v_permlane16_swap_b32_e32 v70, v69
	v_sub_f32_e32 v71, v226, v186
	v_exp_f32_e32 v231, v71
	v_cvt_pk_bf16_f32 v71, v223, v225
	v_cmp_le_i32_e64 s[4:5], v190, v173
	s_waitcnt lgkmcnt(0)
	v_max_f32_e32 v70, v70, v70
	v_max_f32_e32 v74, v69, v70
	v_mov_b32_e32 v185, v74
	s_nop 1
	v_permlane32_swap_b32_e32 v185, v74
	v_exp_f32_e32 v69, v209
	v_cvt_pk_bf16_f32 v70, v213, v221
	s_waitcnt lgkmcnt(0)
	v_max3_f32 v185, v195, v74, v185
	v_sub_f32_e32 v72, v72, v185
	v_exp_f32_e32 v212, v72
	v_sub_f32_e32 v72, v73, v185
	v_exp_f32_e32 v220, v72
	v_sub_f32_e32 v74, v194, v185
	v_exp_f32_e32 v222, v74
	v_pk_add_f32 v[216:217], v[212:213], 0 op_sel_hi:[1,0]
	v_mov_b32_e32 v194, v69
	v_pk_add_f32 v[232:233], v[220:221], v[216:217]
	v_sub_f32_e32 v74, v196, v185
	v_pk_mul_f32 v[62:63], v[62:63], v[194:195] op_sel_hi:[1,0]
	v_pk_mul_f32 v[60:61], v[60:61], v[194:195] op_sel_hi:[1,0]
	v_pk_mul_f32 v[58:59], v[58:59], v[194:195] op_sel_hi:[1,0]
	v_pk_mul_f32 v[56:57], v[56:57], v[194:195] op_sel_hi:[1,0]
	v_pk_mul_f32 v[54:55], v[54:55], v[194:195] op_sel_hi:[1,0]
	v_pk_mul_f32 v[52:53], v[52:53], v[194:195] op_sel_hi:[1,0]
	v_pk_mul_f32 v[50:51], v[50:51], v[194:195] op_sel_hi:[1,0]
	v_pk_mul_f32 v[48:49], v[48:49], v[194:195] op_sel_hi:[1,0]
	v_cvt_pk_bf16_f32 v72, v227, v75
	v_cvt_pk_bf16_f32 v73, v229, v231
	v_exp_f32_e32 v224, v74
	v_sub_f32_e32 v68, v68, v185
	v_mfma_f32_16x16x32_bf16 v[60:63], v[64:67], v[70:73], v[60:63]
	v_cvt_pk_bf16_f32 v216, v212, v220
	v_cvt_pk_bf16_f32 v217, v222, v224
	v_exp_f32_e32 v226, v68
	v_mfma_f32_16x16x32_bf16 v[56:59], v[96:99], v[70:73], v[56:59]
	v_sub_f32_e32 v68, v210, v185
	v_exp_f32_e32 v74, v68
	v_sub_f32_e32 v68, v215, v185
	v_mfma_f32_16x16x32_bf16 v[52:55], v[80:83], v[70:73], v[52:55]
	v_exp_f32_e32 v228, v68
	v_sub_f32_e32 v68, v218, v185
	v_exp_f32_e32 v230, v68
	v_mfma_f32_16x16x32_bf16 v[48:51], v[76:79], v[70:73], v[48:51]
	v_add_f32_e64 v70, v222, v232
	v_add_f32_e64 v71, v223, v233
	v_pk_fma_f32 v[72:73], v[156:157], v[160:161], v[162:163]
	v_pk_add_f32 v[70:71], v[224:225], v[70:71]
	v_mfma_f32_16x16x32_bf16 v[220:223], v[104:107], v[84:87], 0
	v_add_f32_e64 v70, v226, v70
	v_add_f32_e64 v71, v227, v71
	v_cvt_pk_bf16_f32 v218, v226, v74
	v_sub_f32_e32 v68, v195, v185
	v_mfma_f32_16x16x32_bf16 v[84:87], v[120:123], v[84:87], 0
	v_add_f32_e64 v70, v74, v70
	v_add_f32_e64 v71, v75, v71
	v_exp_f32_e32 v68, v68
	v_pk_add_f32 v[70:71], v[228:229], v[70:71]
	v_mfma_f32_16x16x32_bf16 v[160:163], v[100:103], v[108:111], v[220:223]
	v_add_f32_e64 v74, v230, v70
	v_add_f32_e64 v75, v231, v71
	v_pk_add_f32 v[70:71], v[164:165], v[166:167]
	ds_bpermute_b32 v195, v187, v75
	v_mfma_f32_16x16x32_bf16 v[84:87], v[124:127], v[108:111], v[84:87]
	v_sub_f32_e32 v109, v168, v113
	s_nop 1
	v_add_f32_e32 v109, v109, v161
	v_sub_f32_e32 v111, v168, v114
	v_pk_fma_f32 v[70:71], v[150:151], v[158:159], v[70:71]
	v_cndmask_b32_e64 v109, v204, v109, s[4:5]
	v_add_f32_e32 v111, v111, v162
	v_cmp_le_i32_e64 s[4:5], v189, v173
	v_sub_f32_e32 v150, v168, v115
	v_add_f32_e32 v150, v150, v163
	v_cndmask_b32_e64 v111, v204, v111, s[4:5]
	v_cmp_le_i32_e64 s[4:5], v188, v173
	v_sub_f32_e32 v108, v168, v112
	v_add_f32_e32 v108, v108, v160
	v_cndmask_b32_e64 v156, v204, v150, s[4:5]
	v_sub_f32_e32 v150, v168, v116
	v_add_f32_e32 v84, v150, v84
	v_cmp_le_i32_e64 s[4:5], v193, v173
	v_cndmask_b32_e32 v108, v108, v204, vcc
	v_max3_f32 v110, v108, s75, v109
	v_cndmask_b32_e64 v157, v204, v84, s[4:5]
	v_sub_f32_e32 v84, v168, v117
	v_add_f32_e32 v84, v84, v85
	v_cmp_le_i32_e64 s[4:5], v208, v173
	v_sub_f32_e32 v85, v168, v118
	v_max3_f32 v110, v110, v111, v156
	v_cndmask_b32_e64 v158, v204, v84, s[4:5]
	v_add_f32_e32 v85, v85, v86
	v_cmp_le_i32_e64 s[4:5], v197, v173
	v_max3_f32 v84, v110, v157, v158
	ds_bpermute_b32 v194, v187, v74
	v_cndmask_b32_e64 v110, v204, v85, s[4:5]
	v_sub_f32_e32 v85, v168, v119
	v_add_f32_e32 v85, v85, v87
	v_cmp_le_i32_e64 s[4:5], v191, v173
	s_waitcnt lgkmcnt(0)
	v_pk_add_f32 v[74:75], v[74:75], v[194:195]
	v_mov_b32_e32 v151, v75
	s_nop 1
	v_permlane32_swap_b32_e32 v151, v75
	v_cndmask_b32_e64 v159, v204, v85, s[4:5]
	v_max3_f32 v84, v84, v110, v159
	v_mov_b32_e32 v85, v84
	s_nop 1
	v_permlane16_swap_b32_e32 v85, v84
	v_cmp_le_i32_e64 s[4:5], v192, v174
	v_mov_b32_e32 v150, v74
	s_nop 1
	v_permlane32_swap_b32_e32 v150, v74
	v_pk_mul_f32 v[46:47], v[46:47], v[68:69] op_sel_hi:[1,0]
	v_pk_mul_f32 v[44:45], v[44:45], v[68:69] op_sel_hi:[1,0]
	s_waitcnt lgkmcnt(0)
	v_max_f32_e32 v85, v85, v85
	v_max_f32_e32 v84, v84, v85
	v_mov_b32_e32 v85, v84
	s_nop 1
	v_permlane32_swap_b32_e32 v85, v84
	s_waitcnt lgkmcnt(0)
	v_pk_add_f32 v[74:75], v[74:75], v[150:151]
	v_pk_mul_f32 v[38:39], v[38:39], v[68:69] op_sel_hi:[1,0]
	v_pk_mul_f32 v[36:37], v[36:37], v[68:69] op_sel_hi:[1,0]
	v_pk_mul_f32 v[34:35], v[34:35], v[68:69] op_sel_hi:[1,0]
	s_waitcnt lgkmcnt(0)
	v_max3_f32 v167, v211, v84, v85
	v_mfma_f32_16x16x32_bf16 v[84:87], v[104:107], v[88:91], 0
	v_sub_f32_e32 v104, v108, v167
	v_exp_f32_e32 v105, v104
	v_sub_f32_e32 v104, v109, v167
	v_mfma_f32_16x16x32_bf16 v[88:91], v[120:123], v[88:91], 0
	v_exp_f32_e32 v107, v104
	v_sub_f32_e32 v104, v111, v167
	v_exp_f32_e32 v109, v104
	v_mfma_f32_16x16x32_bf16 v[84:87], v[100:103], v[92:95], v[84:87]
	v_sub_f32_e32 v100, v156, v167
	v_exp_f32_e32 v101, v100
	v_sub_f32_e32 v100, v157, v167
	v_mfma_f32_16x16x32_bf16 v[88:91], v[124:127], v[92:95], v[88:91]
	v_sub_f32_e32 v92, v169, v112
	s_nop 2
	v_add_f32_e32 v84, v92, v84
	v_sub_f32_e32 v92, v169, v113
	v_sub_f32_e32 v93, v169, v114
	v_cndmask_b32_e64 v84, v204, v84, s[4:5]
	v_add_f32_e32 v85, v92, v85
	v_cmp_le_i32_e64 s[4:5], v190, v174
	v_add_f32_e32 v86, v93, v86
	v_sub_f32_e32 v93, v169, v115
	v_cndmask_b32_e64 v85, v204, v85, s[4:5]
	v_cmp_le_i32_e64 s[4:5], v189, v174
	v_add_f32_e32 v87, v93, v87
	v_sub_f32_e32 v93, v169, v116
	v_cndmask_b32_e64 v86, v204, v86, s[4:5]
	v_cmp_le_i32_e64 s[4:5], v188, v174
	v_add_f32_e32 v88, v93, v88
	v_sub_f32_e32 v93, v169, v117
	v_max3_f32 v92, v84, s75, v85
	v_cndmask_b32_e64 v87, v204, v87, s[4:5]
	v_cndmask_b32_e32 v88, v88, v204, vcc
	v_add_f32_e32 v89, v93, v89
	v_cmp_le_i32_e32 vcc, v208, v174
	v_max3_f32 v92, v92, v86, v87
	v_sub_f32_e32 v95, v110, v167
	v_cndmask_b32_e32 v94, v204, v89, vcc
	v_max3_f32 v89, v92, v88, v94
	v_sub_f32_e32 v92, v169, v118
	v_add_f32_e32 v90, v92, v90
	v_cmp_le_i32_e32 vcc, v197, v174
	v_sub_f32_e32 v150, v211, v167
	v_exp_f32_e32 v103, v150
	v_cndmask_b32_e32 v92, v204, v90, vcc
	v_sub_f32_e32 v90, v169, v119
	v_add_f32_e32 v90, v90, v91
	v_cmp_le_i32_e32 vcc, v191, v174
	v_sub_f32_e32 v91, v158, v167
	v_exp_f32_e32 v91, v91
	v_cndmask_b32_e32 v102, v204, v90, vcc
	v_max3_f32 v90, v89, v92, v102
	v_mov_b32_e32 v93, v90
	s_nop 1
	v_permlane16_swap_b32_e32 v93, v90
	v_exp_f32_e32 v89, v100
	v_mov_b32_e32 v114, v103
	v_pk_mul_f32 v[32:33], v[32:33], v[68:69] op_sel_hi:[1,0]
	v_pk_mul_f32 v[30:31], v[30:31], v[68:69] op_sel_hi:[1,0]
	s_waitcnt lgkmcnt(0)
	v_max_f32_e32 v93, v93, v93
	v_max_f32_e32 v90, v90, v93
	v_mov_b32_e32 v100, v90
	s_nop 1
	v_permlane32_swap_b32_e32 v100, v90
	v_exp_f32_e32 v93, v95
	v_sub_f32_e32 v95, v159, v167
	v_exp_f32_e32 v95, v95
	v_pk_mul_f32 v[28:29], v[28:29], v[68:69] op_sel_hi:[1,0]
	s_waitcnt lgkmcnt(0)
	v_max3_f32 v166, v214, v90, v100
	v_sub_f32_e32 v84, v84, v166
	v_exp_f32_e32 v104, v84
	v_sub_f32_e32 v84, v85, v166
	v_exp_f32_e32 v106, v84
	v_sub_f32_e32 v84, v86, v166
	v_exp_f32_e32 v108, v84
	v_sub_f32_e32 v84, v87, v166
	v_exp_f32_e32 v100, v84
	v_sub_f32_e32 v86, v88, v166
	v_pk_add_f32 v[84:85], v[104:105], 0 op_sel_hi:[1,0]
	v_exp_f32_e32 v88, v86
	v_sub_f32_e32 v86, v94, v166
	v_pk_add_f32 v[84:85], v[106:107], v[84:85]
	v_exp_f32_e32 v90, v86
	v_sub_f32_e32 v86, v92, v166
	v_pk_add_f32 v[84:85], v[108:109], v[84:85]
	v_exp_f32_e32 v92, v86
	v_sub_f32_e32 v86, v102, v166
	v_pk_add_f32 v[84:85], v[100:101], v[84:85]
	v_exp_f32_e32 v94, v86
	v_pk_add_f32 v[84:85], v[88:89], v[84:85]
	v_cvt_pk_bf16_f32 v86, v89, v91
	v_sub_f32_e32 v89, v214, v166
	v_pk_add_f32 v[84:85], v[90:91], v[84:85]
	v_exp_f32_e32 v102, v89
	v_pk_add_f32 v[84:85], v[92:93], v[84:85]
	v_cvt_pk_bf16_f32 v87, v93, v95
	v_pk_mul_f32 v[42:43], v[42:43], v[114:115] op_sel_hi:[1,0]
	v_pk_add_f32 v[110:111], v[94:95], v[84:85]
	v_mov_b32_e32 v113, v111
	s_nop 1
	v_permlane16_swap_b32_e32 v113, v111
	v_mov_b32_e32 v112, v110
	s_nop 1
	v_permlane16_swap_b32_e32 v112, v110
	v_cvt_pk_bf16_f32 v84, v105, v107
	v_cvt_pk_bf16_f32 v85, v109, v101
	v_pk_mul_f32 v[40:41], v[40:41], v[114:115] op_sel_hi:[1,0]
	v_pk_mul_f32 v[26:27], v[26:27], v[114:115] op_sel_hi:[1,0]
	s_waitcnt lgkmcnt(0)
	v_pk_add_f32 v[110:111], v[110:111], v[112:113]
	ds_bpermute_b32 v113, v149, v111
	ds_bpermute_b32 v112, v149, v110
	v_pk_mul_f32 v[24:25], v[24:25], v[114:115] op_sel_hi:[1,0]
	v_pk_mul_f32 v[22:23], v[22:23], v[114:115] op_sel_hi:[1,0]
	v_pk_mul_f32 v[20:21], v[20:21], v[114:115] op_sel_hi:[1,0]
	v_pk_mul_f32 v[18:19], v[18:19], v[114:115] op_sel_hi:[1,0]
	v_pk_mul_f32 v[16:17], v[16:17], v[114:115] op_sel_hi:[1,0]
	v_pk_mul_f32 v[14:15], v[14:15], v[102:103] op_sel_hi:[1,0]
	v_pk_mul_f32 v[12:13], v[12:13], v[102:103] op_sel_hi:[1,0]
	v_pk_mul_f32 v[10:11], v[10:11], v[102:103] op_sel_hi:[1,0]
	v_pk_mul_f32 v[8:9], v[8:9], v[102:103] op_sel_hi:[1,0]
	v_pk_mul_f32 v[2:3], v[2:3], v[102:103] op_sel_hi:[1,0]
	v_pk_mul_f32 v[0:1], v[0:1], v[102:103] op_sel_hi:[1,0]
	v_pk_mul_f32 v[6:7], v[6:7], v[102:103] op_sel_hi:[1,0]
	v_pk_mul_f32 v[4:5], v[4:5], v[102:103] op_sel_hi:[1,0]
	v_cvt_pk_bf16_f32 v219, v228, v230
	v_mfma_f32_16x16x32_bf16 v[40:43], v[64:67], v[84:87], v[40:43]
	v_fma_f32 v156, v72, v68, v74
	v_fma_f32 v157, v73, v69, v75
	v_mfma_f32_16x16x32_bf16 v[44:47], v[64:67], v[216:219], v[44:47]
	v_mfma_f32_16x16x32_bf16 v[36:39], v[96:99], v[216:219], v[36:39]
	v_mfma_f32_16x16x32_bf16 v[32:35], v[80:83], v[216:219], v[32:35]
	v_mfma_f32_16x16x32_bf16 v[28:31], v[76:79], v[216:219], v[28:31]
	v_mfma_f32_16x16x32_bf16 v[24:27], v[96:99], v[84:87], v[24:27]
	v_mfma_f32_16x16x32_bf16 v[20:23], v[80:83], v[84:87], v[20:23]
	v_mfma_f32_16x16x32_bf16 v[16:19], v[76:79], v[84:87], v[16:19]
	v_cvt_pk_bf16_f32 v84, v104, v106
	v_cvt_pk_bf16_f32 v85, v108, v100
	v_cvt_pk_bf16_f32 v86, v88, v90
	v_cvt_pk_bf16_f32 v87, v92, v94
	s_nop 0
	v_mfma_f32_16x16x32_bf16 v[12:15], v[64:67], v[84:87], v[12:15]
	s_waitcnt lgkmcnt(0)
	v_pk_add_f32 v[64:65], v[110:111], v[112:113]
	s_nop 0
	v_pk_fma_f32 v[150:151], v[70:71], v[102:103], v[64:65]
	v_mfma_f32_16x16x32_bf16 v[8:11], v[96:99], v[84:87], v[8:11]
	v_mfma_f32_16x16x32_bf16 v[0:3], v[80:83], v[84:87], v[0:3]
	v_mfma_f32_16x16x32_bf16 v[4:7], v[76:79], v[84:87], v[4:7]

.LBB0_82:
	v_and_b32_e32 v81, 64, v200
	v_xor_b32_e32 v80, 16, v200
	v_add_u32_e32 v81, 64, v81
	v_cmp_lt_i32_e32 vcc, v80, v81
	v_add_u32_e32 v93, v147, v149
	v_add_u32_e32 v92, v147, v155
	v_cndmask_b32_e32 v80, v200, v80, vcc
	v_lshlrev_b32_e32 v89, 2, v80
	v_xor_b32_e32 v80, 32, v200
	v_cmp_lt_i32_e32 vcc, v80, v81
	ds_read_b128 v[84:87], v92 offset:32768
	v_cmp_gt_i32_e64 s[18:19], v229, v144
	v_cndmask_b32_e32 v80, v200, v80, vcc
	v_lshlrev_b32_e32 v88, 2, v80
	ds_read_b128 v[80:83], v93 offset:32768
	s_waitcnt lgkmcnt(0)
	v_mfma_f32_16x16x32_bf16 v[94:97], v[76:79], v[80:83], 0
	v_cmp_gt_i32_e64 s[16:17], v228, v144
	v_cmp_gt_i32_e64 s[14:15], v227, v144
	v_cmp_gt_i32_e64 s[12:13], v225, v144
	v_mfma_f32_16x16x32_bf16 v[80:83], v[72:75], v[80:83], 0
	v_cmp_gt_i32_e64 s[10:11], v224, v144
	v_cmp_gt_i32_e64 s[8:9], v226, v144
	v_cmp_gt_i32_e64 s[6:7], v223, v144
	v_mfma_f32_16x16x32_bf16 v[94:97], v[68:71], v[84:87], v[94:97]
	v_cmp_gt_i32_e32 vcc, v192, v144
	v_mfma_f32_16x16x32_bf16 v[80:83], v[64:67], v[84:87], v[80:83]
	s_nop 5
	v_max_f32_e32 v84, v94, v94
	v_max_f32_e32 v84, 0xf149f2ca, v84
	v_cndmask_b32_e64 v84, v84, v205, s[18:19]
	v_max_f32_e32 v85, v95, v95
	v_max_f32_e32 v85, v84, v85
	v_cndmask_b32_e64 v84, v85, v84, s[16:17]
	v_max_f32_e32 v85, v96, v96
	v_max_f32_e32 v85, v84, v85
	v_cndmask_b32_e64 v84, v85, v84, s[14:15]
	v_max_f32_e32 v85, v97, v97
	v_max_f32_e32 v85, v84, v85
	v_cndmask_b32_e64 v84, v85, v84, s[12:13]
	v_max_f32_e32 v85, v80, v80
	v_max_f32_e32 v85, v84, v85
	v_cndmask_b32_e64 v84, v85, v84, s[10:11]
	v_max_f32_e32 v85, v84, v84
	v_max_f32_e32 v86, v81, v81
	v_max_f32_e32 v85, v85, v86
	v_cndmask_b32_e64 v84, v85, v84, s[8:9]
	v_max_f32_e32 v85, v84, v84
	v_max_f32_e32 v86, v82, v82
	v_max_f32_e32 v85, v85, v86
	v_cndmask_b32_e64 v84, v85, v84, s[6:7]
	v_max_f32_e32 v85, v84, v84
	v_max_f32_e32 v86, v83, v83
	v_max_f32_e32 v85, v85, v86
	v_cndmask_b32_e32 v84, v85, v84, vcc
	v_mov_b32_e32 v85, v84
	s_nop 1
	v_permlane16_swap_b32_e32 v85, v84
	v_max_f32_e32 v84, v84, v84
	s_waitcnt lgkmcnt(0)
	v_max_f32_e32 v85, v85, v85
	v_max_f32_e32 v84, v84, v85
	v_mov_b32_e32 v85, v84
	s_nop 1
	v_permlane32_swap_b32_e32 v85, v84
	s_waitcnt lgkmcnt(0)
	v_max3_f32 v90, v222, v84, v85
	v_sub_f32_e32 v85, v94, v90
	v_exp_f32_e32 v85, v85
	v_sub_f32_e32 v86, v95, v90
	v_exp_f32_e32 v86, v86
	v_sub_f32_e32 v80, v80, v90
	v_add_f32_e32 v85, 0, v85
	v_cndmask_b32_e64 v85, v85, 0, s[18:19]
	v_cndmask_b32_e64 v86, v86, 0, s[16:17]
	v_add_f32_e32 v85, v86, v85
	v_sub_f32_e32 v86, v96, v90
	v_exp_f32_e32 v86, v86
	v_exp_f32_e32 v80, v80
	v_sub_f32_e32 v81, v81, v90
	v_exp_f32_e32 v81, v81
	v_cndmask_b32_e64 v86, v86, 0, s[14:15]
	v_add_f32_e32 v85, v86, v85
	v_sub_f32_e32 v86, v97, v90
	v_exp_f32_e32 v86, v86
	v_cndmask_b32_e64 v80, v80, 0, s[10:11]
	v_cndmask_b32_e64 v81, v81, 0, s[8:9]
	v_sub_f32_e32 v84, v222, v90
	v_cndmask_b32_e64 v86, v86, 0, s[12:13]
	v_add_f32_e32 v85, v86, v85
	v_add_f32_e32 v80, v80, v85
	v_add_f32_e32 v80, v81, v80
	v_sub_f32_e32 v81, v82, v90
	v_exp_f32_e32 v81, v81
	v_mov_b32_e32 v222, v90
	v_cndmask_b32_e64 v81, v81, 0, s[6:7]
	v_add_f32_e32 v80, v81, v80
	v_sub_f32_e32 v81, v83, v90
	v_exp_f32_e32 v81, v81
	s_nop 0
	v_cndmask_b32_e64 v81, v81, 0, vcc
	v_add_f32_e32 v80, v81, v80
	v_mov_b32_e32 v82, v80
	s_nop 1
	v_permlane16_swap_b32_e32 v82, v80
	v_exp_f32_e32 v81, v84
	s_waitcnt lgkmcnt(0)
	v_add_f32_e32 v80, v80, v82
	v_mov_b32_e32 v82, v80
	s_nop 1
	v_permlane32_swap_b32_e32 v82, v80
	s_waitcnt lgkmcnt(0)
	v_add_f32_e32 v91, v80, v82
	v_fmac_f32_e32 v91, v221, v81
	ds_read_b128 v[84:87], v93 offset:40960
	ds_read_b128 v[80:83], v92 offset:40960
	s_waitcnt lgkmcnt(1)
	v_mfma_f32_16x16x32_bf16 v[94:97], v[76:79], v[84:87], 0
	v_mov_b32_e32 v221, v91
	v_mfma_f32_16x16x32_bf16 v[84:87], v[72:75], v[84:87], 0
	s_waitcnt lgkmcnt(0)
	v_mfma_f32_16x16x32_bf16 v[94:97], v[68:71], v[80:83], v[94:97]
	v_mfma_f32_16x16x32_bf16 v[82:85], v[64:67], v[80:83], v[84:87]
	s_nop 6
	v_max_f32_e32 v80, v94, v94
	v_max_f32_e32 v80, 0xf149f2ca, v80
	v_cndmask_b32_e64 v80, v80, v205, s[18:19]
	v_max_f32_e32 v81, v95, v95
	v_max_f32_e32 v81, v80, v81
	v_cndmask_b32_e64 v80, v81, v80, s[16:17]
	v_max_f32_e32 v81, v96, v96
	v_max_f32_e32 v81, v80, v81
	v_cndmask_b32_e64 v80, v81, v80, s[14:15]
	v_max_f32_e32 v81, v97, v97
	v_max_f32_e32 v81, v80, v81
	v_cndmask_b32_e64 v80, v81, v80, s[12:13]
	v_max_f32_e32 v81, v82, v82
	v_max_f32_e32 v81, v80, v81
	v_cndmask_b32_e64 v80, v81, v80, s[10:11]
	v_max_f32_e32 v81, v80, v80
	v_max_f32_e32 v86, v83, v83
	v_max_f32_e32 v81, v81, v86
	v_cndmask_b32_e64 v80, v81, v80, s[8:9]
	v_max_f32_e32 v81, v80, v80
	v_max_f32_e32 v86, v84, v84
	v_max_f32_e32 v81, v81, v86
	v_cndmask_b32_e64 v80, v81, v80, s[6:7]
	v_max_f32_e32 v81, v80, v80
	v_max_f32_e32 v86, v85, v85
	v_max_f32_e32 v81, v81, v86
	v_cndmask_b32_e32 v80, v81, v80, vcc
	v_mov_b32_e32 v81, v80
	s_nop 1
	v_permlane16_swap_b32_e32 v81, v80
	v_max_f32_e32 v80, v80, v80
	s_waitcnt lgkmcnt(0)
	v_max_f32_e32 v81, v81, v81
	v_max_f32_e32 v80, v80, v81
	v_mov_b32_e32 v81, v80
	s_nop 1
	v_permlane32_swap_b32_e32 v81, v80
	s_waitcnt lgkmcnt(0)
	v_max3_f32 v80, v220, v80, v81
	v_sub_f32_e32 v86, v94, v80
	v_exp_f32_e32 v86, v86
	v_sub_f32_e32 v87, v95, v80
	v_exp_f32_e32 v87, v87
	v_sub_f32_e32 v82, v82, v80
	v_add_f32_e32 v86, 0, v86
	v_cndmask_b32_e64 v86, v86, 0, s[18:19]
	v_cndmask_b32_e64 v87, v87, 0, s[16:17]
	v_add_f32_e32 v86, v87, v86
	v_sub_f32_e32 v87, v96, v80
	v_exp_f32_e32 v87, v87
	v_exp_f32_e32 v82, v82
	v_sub_f32_e32 v83, v83, v80
	v_exp_f32_e32 v83, v83
	v_cndmask_b32_e64 v87, v87, 0, s[14:15]
	v_add_f32_e32 v86, v87, v86
	v_sub_f32_e32 v87, v97, v80
	v_exp_f32_e32 v87, v87
	v_cndmask_b32_e64 v82, v82, 0, s[10:11]
	v_cndmask_b32_e64 v83, v83, 0, s[8:9]
	v_sub_f32_e32 v81, v220, v80
	v_cndmask_b32_e64 v87, v87, 0, s[12:13]
	v_add_f32_e32 v86, v87, v86
	v_add_f32_e32 v82, v82, v86
	v_add_f32_e32 v82, v83, v82
	v_sub_f32_e32 v83, v84, v80
	v_exp_f32_e32 v83, v83
	v_mov_b32_e32 v220, v80
	v_cndmask_b32_e64 v83, v83, 0, s[6:7]
	v_add_f32_e32 v82, v83, v82
	v_sub_f32_e32 v83, v85, v80
	v_exp_f32_e32 v83, v83
	s_nop 0
	v_cndmask_b32_e64 v83, v83, 0, vcc
	v_add_f32_e32 v82, v83, v82
	v_exp_f32_e32 v83, v81
	v_mov_b32_e32 v81, v82
	s_nop 1
	v_permlane16_swap_b32_e32 v81, v82
	s_waitcnt lgkmcnt(0)
	v_add_f32_e32 v81, v82, v81
	v_mov_b32_e32 v82, v81
	s_nop 1
	v_permlane32_swap_b32_e32 v82, v81
	s_waitcnt lgkmcnt(0)
	v_add_f32_e32 v81, v81, v82
	v_fmac_f32_e32 v81, v219, v83
	ds_read_b128 v[82:85], v93 offset:49152
	ds_read_b128 v[94:97], v92 offset:49152
	s_waitcnt lgkmcnt(1)
	v_mfma_f32_16x16x32_bf16 v[98:101], v[76:79], v[82:85], 0
	v_mov_b32_e32 v219, v81
	v_mfma_f32_16x16x32_bf16 v[82:85], v[72:75], v[82:85], 0
	s_waitcnt lgkmcnt(0)
	v_mfma_f32_16x16x32_bf16 v[98:101], v[68:71], v[94:97], v[98:101]
	v_mfma_f32_16x16x32_bf16 v[84:87], v[64:67], v[94:97], v[82:85]
	s_nop 6
	v_max_f32_e32 v82, v98, v98
	v_max_f32_e32 v82, 0xf149f2ca, v82
	v_cndmask_b32_e64 v82, v82, v205, s[18:19]
	v_max_f32_e32 v83, v99, v99
	v_max_f32_e32 v83, v82, v83
	v_cndmask_b32_e64 v82, v83, v82, s[16:17]
	v_max_f32_e32 v83, v100, v100
	v_max_f32_e32 v83, v82, v83
	v_cndmask_b32_e64 v82, v83, v82, s[14:15]
	v_max_f32_e32 v83, v101, v101
	v_max_f32_e32 v83, v82, v83
	v_cndmask_b32_e64 v82, v83, v82, s[12:13]
	v_max_f32_e32 v83, v84, v84
	v_max_f32_e32 v83, v82, v83
	v_cndmask_b32_e64 v82, v83, v82, s[10:11]
	v_max_f32_e32 v83, v82, v82
	v_max_f32_e32 v94, v85, v85
	v_max_f32_e32 v83, v83, v94
	v_cndmask_b32_e64 v82, v83, v82, s[8:9]
	v_max_f32_e32 v83, v82, v82
	v_max_f32_e32 v94, v86, v86
	v_max_f32_e32 v83, v83, v94
	v_cndmask_b32_e64 v82, v83, v82, s[6:7]
	v_max_f32_e32 v83, v82, v82
	v_max_f32_e32 v94, v87, v87
	v_max_f32_e32 v83, v83, v94
	v_cndmask_b32_e32 v82, v83, v82, vcc
	v_mov_b32_e32 v83, v82
	s_nop 1
	v_permlane16_swap_b32_e32 v83, v82
	v_max_f32_e32 v82, v82, v82
	s_waitcnt lgkmcnt(0)
	v_max_f32_e32 v83, v83, v83
	v_max_f32_e32 v82, v82, v83
	v_mov_b32_e32 v83, v82
	s_nop 1
	v_permlane32_swap_b32_e32 v83, v82
	s_waitcnt lgkmcnt(0)
	v_max3_f32 v82, v218, v82, v83
	v_sub_f32_e32 v94, v98, v82
	v_exp_f32_e32 v94, v94
	v_sub_f32_e32 v95, v99, v82
	v_exp_f32_e32 v95, v95
	v_sub_f32_e32 v84, v84, v82
	v_add_f32_e32 v94, 0, v94
	v_cndmask_b32_e64 v94, v94, 0, s[18:19]
	v_cndmask_b32_e64 v95, v95, 0, s[16:17]
	v_add_f32_e32 v94, v95, v94
	v_sub_f32_e32 v95, v100, v82
	v_exp_f32_e32 v95, v95
	v_exp_f32_e32 v84, v84
	v_sub_f32_e32 v85, v85, v82
	v_exp_f32_e32 v85, v85
	v_cndmask_b32_e64 v95, v95, 0, s[14:15]
	v_add_f32_e32 v94, v95, v94
	v_sub_f32_e32 v95, v101, v82
	v_exp_f32_e32 v95, v95
	v_cndmask_b32_e64 v84, v84, 0, s[10:11]
	v_cndmask_b32_e64 v85, v85, 0, s[8:9]
	v_sub_f32_e32 v83, v218, v82
	v_cndmask_b32_e64 v95, v95, 0, s[12:13]
	v_add_f32_e32 v94, v95, v94
	v_add_f32_e32 v84, v84, v94
	v_add_f32_e32 v84, v85, v84
	v_sub_f32_e32 v85, v86, v82
	v_exp_f32_e32 v85, v85
	v_mov_b32_e32 v218, v82
	v_cndmask_b32_e64 v85, v85, 0, s[6:7]
	v_add_f32_e32 v84, v85, v84
	v_sub_f32_e32 v85, v87, v82
	v_exp_f32_e32 v85, v85
	s_nop 0
	v_cndmask_b32_e64 v85, v85, 0, vcc
	v_add_f32_e32 v84, v85, v84
	v_exp_f32_e32 v85, v83
	v_mov_b32_e32 v83, v84
	s_nop 1
	v_permlane16_swap_b32_e32 v83, v84
	s_waitcnt lgkmcnt(0)
	v_add_f32_e32 v83, v84, v83
	v_mov_b32_e32 v84, v83
	s_nop 1
	v_permlane32_swap_b32_e32 v84, v83
	s_waitcnt lgkmcnt(0)
	v_add_f32_e32 v83, v83, v84
	v_fmac_f32_e32 v83, v217, v85
	ds_read_b128 v[84:87], v93 offset:57344
	ds_read_b128 v[92:95], v92 offset:57344
	s_waitcnt lgkmcnt(1)
	v_mfma_f32_16x16x32_bf16 v[76:79], v[76:79], v[84:87], 0
	v_mov_b32_e32 v217, v83
	v_mfma_f32_16x16x32_bf16 v[72:75], v[72:75], v[84:87], 0
	s_waitcnt lgkmcnt(0)
	v_mfma_f32_16x16x32_bf16 v[68:71], v[68:71], v[92:95], v[76:79]
	v_mfma_f32_16x16x32_bf16 v[64:67], v[64:67], v[92:95], v[72:75]
	s_nop 6
	v_max_f32_e32 v72, v68, v68
	v_max_f32_e32 v72, 0xf149f2ca, v72
	v_cndmask_b32_e64 v72, v72, v205, s[18:19]
	v_max_f32_e32 v73, v69, v69
	v_max_f32_e32 v73, v72, v73
	v_cndmask_b32_e64 v72, v73, v72, s[16:17]
	v_max_f32_e32 v73, v70, v70
	v_max_f32_e32 v73, v72, v73
	v_cndmask_b32_e64 v72, v73, v72, s[14:15]
	v_max_f32_e32 v73, v71, v71
	v_max_f32_e32 v73, v72, v73
	v_cndmask_b32_e64 v72, v73, v72, s[12:13]
	v_max_f32_e32 v73, v64, v64
	v_max_f32_e32 v73, v72, v73
	v_cndmask_b32_e64 v72, v73, v72, s[10:11]
	v_max_f32_e32 v73, v72, v72
	v_max_f32_e32 v74, v65, v65
	v_max_f32_e32 v73, v73, v74
	v_cndmask_b32_e64 v72, v73, v72, s[8:9]
	v_max_f32_e32 v73, v72, v72
	v_max_f32_e32 v74, v66, v66
	v_max_f32_e32 v73, v73, v74
	v_cndmask_b32_e64 v72, v73, v72, s[6:7]
	v_max_f32_e32 v73, v72, v72
	v_max_f32_e32 v74, v67, v67
	v_max_f32_e32 v73, v73, v74
	v_cndmask_b32_e32 v72, v73, v72, vcc
	v_mov_b32_e32 v73, v72
	s_nop 1
	v_permlane16_swap_b32_e32 v73, v72
	v_max_f32_e32 v72, v72, v72
	s_waitcnt lgkmcnt(0)
	v_max_f32_e32 v73, v73, v73
	v_max_f32_e32 v72, v72, v73
	v_mov_b32_e32 v73, v72
	s_nop 1
	v_permlane32_swap_b32_e32 v73, v72
	s_waitcnt lgkmcnt(0)
	v_max3_f32 v72, v196, v72, v73
	v_sub_f32_e32 v68, v68, v72
	v_exp_f32_e32 v68, v68
	v_sub_f32_e32 v69, v69, v72
	v_exp_f32_e32 v69, v69
	v_sub_f32_e32 v64, v64, v72
	v_add_f32_e32 v68, 0, v68
	v_cndmask_b32_e64 v68, v68, 0, s[18:19]
	v_cndmask_b32_e64 v69, v69, 0, s[16:17]
	v_add_f32_e32 v68, v69, v68
	v_sub_f32_e32 v69, v70, v72
	v_exp_f32_e32 v69, v69
	v_exp_f32_e32 v64, v64
	v_sub_f32_e32 v65, v65, v72
	v_exp_f32_e32 v65, v65
	v_cndmask_b32_e64 v69, v69, 0, s[14:15]
	v_add_f32_e32 v68, v69, v68
	v_sub_f32_e32 v69, v71, v72
	v_exp_f32_e32 v69, v69
	v_cndmask_b32_e64 v64, v64, 0, s[10:11]
	v_cndmask_b32_e64 v65, v65, 0, s[8:9]
	v_sub_f32_e32 v73, v196, v72
	v_cndmask_b32_e64 v69, v69, 0, s[12:13]
	v_add_f32_e32 v68, v69, v68
	v_add_f32_e32 v64, v64, v68
	v_add_f32_e32 v64, v65, v64
	v_sub_f32_e32 v65, v66, v72
	v_exp_f32_e32 v65, v65
	v_mov_b32_e32 v196, v72
	v_cndmask_b32_e64 v65, v65, 0, s[6:7]
	v_add_f32_e32 v64, v65, v64
	v_sub_f32_e32 v65, v67, v72
	v_exp_f32_e32 v65, v65
	s_nop 0
	v_cndmask_b32_e64 v65, v65, 0, vcc
	v_add_f32_e32 v64, v65, v64
	v_mov_b32_e32 v66, v64
	s_nop 1
	v_permlane16_swap_b32_e32 v66, v64
	v_exp_f32_e32 v65, v73
	s_waitcnt lgkmcnt(0)
	v_add_f32_e32 v64, v64, v66
	ds_bpermute_b32 v66, v88, v64
	s_waitcnt lgkmcnt(0)
	v_add_f32_e32 v64, v64, v66
	v_fmac_f32_e32 v64, v187, v65
	v_mov_b32_e32 v187, v64

.LBB0_86:
	s_andn2_b64 vcc, exec, s[24:25]
	s_cbranch_vccnz .LBB0_88
	v_and_b32_e32 v81, 64, v200
	v_xor_b32_e32 v80, 16, v200
	v_add_u32_e32 v81, 64, v81
	v_cmp_lt_i32_e32 vcc, v80, v81
	v_add_u32_e32 v93, v147, v149
	v_add_u32_e32 v92, v147, v155
	v_cndmask_b32_e32 v80, v200, v80, vcc
	v_lshlrev_b32_e32 v89, 2, v80
	v_xor_b32_e32 v80, 32, v200
	v_cmp_lt_i32_e32 vcc, v80, v81
	ds_read_b128 v[84:87], v92 offset:32768
	v_cmp_gt_i32_e64 s[18:19], v232, v144
	v_cndmask_b32_e32 v80, v200, v80, vcc
	v_lshlrev_b32_e32 v88, 2, v80
	ds_read_b128 v[80:83], v93 offset:32768
	s_waitcnt lgkmcnt(0)
	v_mfma_f32_16x16x32_bf16 v[94:97], v[76:79], v[80:83], 0
	v_cmp_gt_i32_e64 s[16:17], v231, v144
	v_cmp_gt_i32_e64 s[14:15], v230, v144
	v_cmp_gt_i32_e64 s[12:13], v229, v144
	v_mfma_f32_16x16x32_bf16 v[80:83], v[72:75], v[80:83], 0
	v_cmp_gt_i32_e64 s[10:11], v228, v144
	v_cmp_gt_i32_e64 s[8:9], v227, v144
	v_cmp_gt_i32_e64 s[6:7], v226, v144
	v_mfma_f32_16x16x32_bf16 v[94:97], v[68:71], v[84:87], v[94:97]
	v_cmp_gt_i32_e32 vcc, v225, v144
	v_mfma_f32_16x16x32_bf16 v[80:83], v[64:67], v[84:87], v[80:83]
	s_nop 5
	v_max_f32_e32 v84, v94, v94
	v_max_f32_e32 v84, 0xf149f2ca, v84
	v_cndmask_b32_e64 v84, v84, v205, s[18:19]
	v_max_f32_e32 v85, v95, v95
	v_max_f32_e32 v85, v84, v85
	v_cndmask_b32_e64 v84, v85, v84, s[16:17]
	v_max_f32_e32 v85, v96, v96
	v_max_f32_e32 v85, v84, v85
	v_cndmask_b32_e64 v84, v85, v84, s[14:15]
	v_max_f32_e32 v85, v97, v97
	v_max_f32_e32 v85, v84, v85
	v_cndmask_b32_e64 v84, v85, v84, s[12:13]
	v_max_f32_e32 v85, v80, v80
	v_max_f32_e32 v85, v84, v85
	v_cndmask_b32_e64 v84, v85, v84, s[10:11]
	v_max_f32_e32 v85, v84, v84
	v_max_f32_e32 v86, v81, v81
	v_max_f32_e32 v85, v85, v86
	v_cndmask_b32_e64 v84, v85, v84, s[8:9]
	v_max_f32_e32 v85, v84, v84
	v_max_f32_e32 v86, v82, v82
	v_max_f32_e32 v85, v85, v86
	v_cndmask_b32_e64 v84, v85, v84, s[6:7]
	v_max_f32_e32 v85, v84, v84
	v_max_f32_e32 v86, v83, v83
	v_max_f32_e32 v85, v85, v86
	v_cndmask_b32_e32 v84, v85, v84, vcc
	v_mov_b32_e32 v85, v84
	s_nop 1
	v_permlane16_swap_b32_e32 v85, v84
	v_max_f32_e32 v84, v84, v84
	s_waitcnt lgkmcnt(0)
	v_max_f32_e32 v85, v85, v85
	v_max_f32_e32 v84, v84, v85
	v_mov_b32_e32 v85, v84
	s_nop 1
	v_permlane32_swap_b32_e32 v85, v84
	s_waitcnt lgkmcnt(0)
	v_max3_f32 v90, v222, v84, v85
	v_sub_f32_e32 v85, v94, v90
	v_exp_f32_e32 v85, v85
	v_sub_f32_e32 v86, v95, v90
	v_exp_f32_e32 v86, v86
	v_sub_f32_e32 v80, v80, v90
	v_add_f32_e32 v85, 0, v85
	v_cndmask_b32_e64 v85, v85, 0, s[18:19]
	v_cndmask_b32_e64 v86, v86, 0, s[16:17]
	v_add_f32_e32 v85, v86, v85
	v_sub_f32_e32 v86, v96, v90
	v_exp_f32_e32 v86, v86
	v_exp_f32_e32 v80, v80
	v_sub_f32_e32 v81, v81, v90
	v_exp_f32_e32 v81, v81
	v_cndmask_b32_e64 v86, v86, 0, s[14:15]
	v_add_f32_e32 v85, v86, v85
	v_sub_f32_e32 v86, v97, v90
	v_exp_f32_e32 v86, v86
	v_cndmask_b32_e64 v80, v80, 0, s[10:11]
	v_cndmask_b32_e64 v81, v81, 0, s[8:9]
	v_sub_f32_e32 v84, v222, v90
	v_cndmask_b32_e64 v86, v86, 0, s[12:13]
	v_add_f32_e32 v85, v86, v85
	v_add_f32_e32 v80, v80, v85
	v_add_f32_e32 v80, v81, v80
	v_sub_f32_e32 v81, v82, v90
	v_exp_f32_e32 v81, v81
	v_mov_b32_e32 v222, v90
	v_cndmask_b32_e64 v81, v81, 0, s[6:7]
	v_add_f32_e32 v80, v81, v80
	v_sub_f32_e32 v81, v83, v90
	v_exp_f32_e32 v81, v81
	s_nop 0
	v_cndmask_b32_e64 v81, v81, 0, vcc
	v_add_f32_e32 v80, v81, v80
	v_mov_b32_e32 v82, v80
	s_nop 1
	v_permlane16_swap_b32_e32 v82, v80
	v_exp_f32_e32 v81, v84
	s_waitcnt lgkmcnt(0)
	v_add_f32_e32 v80, v80, v82
	v_mov_b32_e32 v82, v80
	s_nop 1
	v_permlane32_swap_b32_e32 v82, v80
	s_waitcnt lgkmcnt(0)
	v_add_f32_e32 v91, v80, v82
	v_fmac_f32_e32 v91, v221, v81
	ds_read_b128 v[84:87], v93 offset:40960
	ds_read_b128 v[80:83], v92 offset:40960
	s_waitcnt lgkmcnt(1)
	v_mfma_f32_16x16x32_bf16 v[94:97], v[76:79], v[84:87], 0
	v_mov_b32_e32 v221, v91
	v_mfma_f32_16x16x32_bf16 v[84:87], v[72:75], v[84:87], 0
	s_waitcnt lgkmcnt(0)
	v_mfma_f32_16x16x32_bf16 v[94:97], v[68:71], v[80:83], v[94:97]
	v_mfma_f32_16x16x32_bf16 v[82:85], v[64:67], v[80:83], v[84:87]
	s_nop 6
	v_max_f32_e32 v80, v94, v94
	v_max_f32_e32 v80, 0xf149f2ca, v80
	v_cndmask_b32_e64 v80, v80, v205, s[18:19]
	v_max_f32_e32 v81, v95, v95
	v_max_f32_e32 v81, v80, v81
	v_cndmask_b32_e64 v80, v81, v80, s[16:17]
	v_max_f32_e32 v81, v96, v96
	v_max_f32_e32 v81, v80, v81
	v_cndmask_b32_e64 v80, v81, v80, s[14:15]
	v_max_f32_e32 v81, v97, v97
	v_max_f32_e32 v81, v80, v81
	v_cndmask_b32_e64 v80, v81, v80, s[12:13]
	v_max_f32_e32 v81, v82, v82
	v_max_f32_e32 v81, v80, v81
	v_cndmask_b32_e64 v80, v81, v80, s[10:11]
	v_max_f32_e32 v81, v80, v80
	v_max_f32_e32 v86, v83, v83
	v_max_f32_e32 v81, v81, v86
	v_cndmask_b32_e64 v80, v81, v80, s[8:9]
	v_max_f32_e32 v81, v80, v80
	v_max_f32_e32 v86, v84, v84
	v_max_f32_e32 v81, v81, v86
	v_cndmask_b32_e64 v80, v81, v80, s[6:7]
	v_max_f32_e32 v81, v80, v80
	v_max_f32_e32 v86, v85, v85
	v_max_f32_e32 v81, v81, v86
	v_cndmask_b32_e32 v80, v81, v80, vcc
	v_mov_b32_e32 v81, v80
	s_nop 1
	v_permlane16_swap_b32_e32 v81, v80
	v_max_f32_e32 v80, v80, v80
	s_waitcnt lgkmcnt(0)
	v_max_f32_e32 v81, v81, v81
	v_max_f32_e32 v80, v80, v81
	v_mov_b32_e32 v81, v80
	s_nop 1
	v_permlane32_swap_b32_e32 v81, v80
	s_waitcnt lgkmcnt(0)
	v_max3_f32 v80, v220, v80, v81
	v_sub_f32_e32 v86, v94, v80
	v_exp_f32_e32 v86, v86
	v_sub_f32_e32 v87, v95, v80
	v_exp_f32_e32 v87, v87
	v_sub_f32_e32 v82, v82, v80
	v_add_f32_e32 v86, 0, v86
	v_cndmask_b32_e64 v86, v86, 0, s[18:19]
	v_cndmask_b32_e64 v87, v87, 0, s[16:17]
	v_add_f32_e32 v86, v87, v86
	v_sub_f32_e32 v87, v96, v80
	v_exp_f32_e32 v87, v87
	v_exp_f32_e32 v82, v82
	v_sub_f32_e32 v83, v83, v80
	v_exp_f32_e32 v83, v83
	v_cndmask_b32_e64 v87, v87, 0, s[14:15]
	v_add_f32_e32 v86, v87, v86
	v_sub_f32_e32 v87, v97, v80
	v_exp_f32_e32 v87, v87
	v_cndmask_b32_e64 v82, v82, 0, s[10:11]
	v_cndmask_b32_e64 v83, v83, 0, s[8:9]
	v_sub_f32_e32 v81, v220, v80
	v_cndmask_b32_e64 v87, v87, 0, s[12:13]
	v_add_f32_e32 v86, v87, v86
	v_add_f32_e32 v82, v82, v86
	v_add_f32_e32 v82, v83, v82
	v_sub_f32_e32 v83, v84, v80
	v_exp_f32_e32 v83, v83
	v_mov_b32_e32 v220, v80
	v_cndmask_b32_e64 v83, v83, 0, s[6:7]
	v_add_f32_e32 v82, v83, v82
	v_sub_f32_e32 v83, v85, v80
	v_exp_f32_e32 v83, v83
	s_nop 0
	v_cndmask_b32_e64 v83, v83, 0, vcc
	v_add_f32_e32 v82, v83, v82
	v_exp_f32_e32 v83, v81
	v_mov_b32_e32 v81, v82
	s_nop 1
	v_permlane16_swap_b32_e32 v81, v82
	s_waitcnt lgkmcnt(0)
	v_add_f32_e32 v81, v82, v81
	v_mov_b32_e32 v82, v81
	s_nop 1
	v_permlane32_swap_b32_e32 v82, v81
	s_waitcnt lgkmcnt(0)
	v_add_f32_e32 v81, v81, v82
	v_fmac_f32_e32 v81, v219, v83
	ds_read_b128 v[82:85], v93 offset:49152
	ds_read_b128 v[94:97], v92 offset:49152
	s_waitcnt lgkmcnt(1)
	v_mfma_f32_16x16x32_bf16 v[98:101], v[76:79], v[82:85], 0
	v_mov_b32_e32 v219, v81
	v_mfma_f32_16x16x32_bf16 v[82:85], v[72:75], v[82:85], 0
	s_waitcnt lgkmcnt(0)
	v_mfma_f32_16x16x32_bf16 v[98:101], v[68:71], v[94:97], v[98:101]
	v_mfma_f32_16x16x32_bf16 v[84:87], v[64:67], v[94:97], v[82:85]
	s_nop 6
	v_max_f32_e32 v82, v98, v98
	v_max_f32_e32 v82, 0xf149f2ca, v82
	v_cndmask_b32_e64 v82, v82, v205, s[18:19]
	v_max_f32_e32 v83, v99, v99
	v_max_f32_e32 v83, v82, v83
	v_cndmask_b32_e64 v82, v83, v82, s[16:17]
	v_max_f32_e32 v83, v100, v100
	v_max_f32_e32 v83, v82, v83
	v_cndmask_b32_e64 v82, v83, v82, s[14:15]
	v_max_f32_e32 v83, v101, v101
	v_max_f32_e32 v83, v82, v83
	v_cndmask_b32_e64 v82, v83, v82, s[12:13]
	v_max_f32_e32 v83, v84, v84
	v_max_f32_e32 v83, v82, v83
	v_cndmask_b32_e64 v82, v83, v82, s[10:11]
	v_max_f32_e32 v83, v82, v82
	v_max_f32_e32 v94, v85, v85
	v_max_f32_e32 v83, v83, v94
	v_cndmask_b32_e64 v82, v83, v82, s[8:9]
	v_max_f32_e32 v83, v82, v82
	v_max_f32_e32 v94, v86, v86
	v_max_f32_e32 v83, v83, v94
	v_cndmask_b32_e64 v82, v83, v82, s[6:7]
	v_max_f32_e32 v83, v82, v82
	v_max_f32_e32 v94, v87, v87
	v_max_f32_e32 v83, v83, v94
	v_cndmask_b32_e32 v82, v83, v82, vcc
	v_mov_b32_e32 v83, v82
	s_nop 1
	v_permlane16_swap_b32_e32 v83, v82
	v_max_f32_e32 v82, v82, v82
	s_waitcnt lgkmcnt(0)
	v_max_f32_e32 v83, v83, v83
	v_max_f32_e32 v82, v82, v83
	v_mov_b32_e32 v83, v82
	s_nop 1
	v_permlane32_swap_b32_e32 v83, v82
	s_waitcnt lgkmcnt(0)
	v_max3_f32 v82, v218, v82, v83
	v_sub_f32_e32 v94, v98, v82
	v_exp_f32_e32 v94, v94
	v_sub_f32_e32 v95, v99, v82
	v_exp_f32_e32 v95, v95
	v_sub_f32_e32 v84, v84, v82
	v_add_f32_e32 v94, 0, v94
	v_cndmask_b32_e64 v94, v94, 0, s[18:19]
	v_cndmask_b32_e64 v95, v95, 0, s[16:17]
	v_add_f32_e32 v94, v95, v94
	v_sub_f32_e32 v95, v100, v82
	v_exp_f32_e32 v95, v95
	v_exp_f32_e32 v84, v84
	v_sub_f32_e32 v85, v85, v82
	v_exp_f32_e32 v85, v85
	v_cndmask_b32_e64 v95, v95, 0, s[14:15]
	v_add_f32_e32 v94, v95, v94
	v_sub_f32_e32 v95, v101, v82
	v_exp_f32_e32 v95, v95
	v_cndmask_b32_e64 v84, v84, 0, s[10:11]
	v_cndmask_b32_e64 v85, v85, 0, s[8:9]
	v_sub_f32_e32 v83, v218, v82
	v_cndmask_b32_e64 v95, v95, 0, s[12:13]
	v_add_f32_e32 v94, v95, v94
	v_add_f32_e32 v84, v84, v94
	v_add_f32_e32 v84, v85, v84
	v_sub_f32_e32 v85, v86, v82
	v_exp_f32_e32 v85, v85
	v_mov_b32_e32 v218, v82
	v_cndmask_b32_e64 v85, v85, 0, s[6:7]
	v_add_f32_e32 v84, v85, v84
	v_sub_f32_e32 v85, v87, v82
	v_exp_f32_e32 v85, v85
	s_nop 0
	v_cndmask_b32_e64 v85, v85, 0, vcc
	v_add_f32_e32 v84, v85, v84
	v_exp_f32_e32 v85, v83
	v_mov_b32_e32 v83, v84
	s_nop 1
	v_permlane16_swap_b32_e32 v83, v84
	s_waitcnt lgkmcnt(0)
	v_add_f32_e32 v83, v84, v83
	v_mov_b32_e32 v84, v83
	s_nop 1
	v_permlane32_swap_b32_e32 v84, v83
	s_waitcnt lgkmcnt(0)
	v_add_f32_e32 v83, v83, v84
	v_fmac_f32_e32 v83, v217, v85
	ds_read_b128 v[84:87], v93 offset:57344
	ds_read_b128 v[92:95], v92 offset:57344
	s_waitcnt lgkmcnt(1)
	v_mfma_f32_16x16x32_bf16 v[76:79], v[76:79], v[84:87], 0
	v_mov_b32_e32 v217, v83
	v_mfma_f32_16x16x32_bf16 v[72:75], v[72:75], v[84:87], 0
	s_waitcnt lgkmcnt(0)
	v_mfma_f32_16x16x32_bf16 v[68:71], v[68:71], v[92:95], v[76:79]
	v_mfma_f32_16x16x32_bf16 v[64:67], v[64:67], v[92:95], v[72:75]
	s_nop 6
	v_max_f32_e32 v72, v68, v68
	v_max_f32_e32 v72, 0xf149f2ca, v72
	v_cndmask_b32_e64 v72, v72, v205, s[18:19]
	v_max_f32_e32 v73, v69, v69
	v_max_f32_e32 v73, v72, v73
	v_cndmask_b32_e64 v72, v73, v72, s[16:17]
	v_max_f32_e32 v73, v70, v70
	v_max_f32_e32 v73, v72, v73
	v_cndmask_b32_e64 v72, v73, v72, s[14:15]
	v_max_f32_e32 v73, v71, v71
	v_max_f32_e32 v73, v72, v73
	v_cndmask_b32_e64 v72, v73, v72, s[12:13]
	v_max_f32_e32 v73, v64, v64
	v_max_f32_e32 v73, v72, v73
	v_cndmask_b32_e64 v72, v73, v72, s[10:11]
	v_max_f32_e32 v73, v72, v72
	v_max_f32_e32 v74, v65, v65
	v_max_f32_e32 v73, v73, v74
	v_cndmask_b32_e64 v72, v73, v72, s[8:9]
	v_max_f32_e32 v73, v72, v72
	v_max_f32_e32 v74, v66, v66
	v_max_f32_e32 v73, v73, v74
	v_cndmask_b32_e64 v72, v73, v72, s[6:7]
	v_max_f32_e32 v73, v72, v72
	v_max_f32_e32 v74, v67, v67
	v_max_f32_e32 v73, v73, v74
	v_cndmask_b32_e32 v72, v73, v72, vcc
	v_mov_b32_e32 v73, v72
	s_nop 1
	v_permlane16_swap_b32_e32 v73, v72
	v_max_f32_e32 v72, v72, v72
	s_waitcnt lgkmcnt(0)
	v_max_f32_e32 v73, v73, v73
	v_max_f32_e32 v72, v72, v73
	v_mov_b32_e32 v73, v72
	s_nop 1
	v_permlane32_swap_b32_e32 v73, v72
	s_waitcnt lgkmcnt(0)
	v_max3_f32 v72, v196, v72, v73
	v_sub_f32_e32 v68, v68, v72
	v_exp_f32_e32 v68, v68
	v_sub_f32_e32 v69, v69, v72
	v_exp_f32_e32 v69, v69
	v_sub_f32_e32 v64, v64, v72
	v_add_f32_e32 v68, 0, v68
	v_cndmask_b32_e64 v68, v68, 0, s[18:19]
	v_cndmask_b32_e64 v69, v69, 0, s[16:17]
	v_add_f32_e32 v68, v69, v68
	v_sub_f32_e32 v69, v70, v72
	v_exp_f32_e32 v69, v69
	v_exp_f32_e32 v64, v64
	v_sub_f32_e32 v65, v65, v72
	v_exp_f32_e32 v65, v65
	v_cndmask_b32_e64 v69, v69, 0, s[14:15]
	v_add_f32_e32 v68, v69, v68
	v_sub_f32_e32 v69, v71, v72
	v_exp_f32_e32 v69, v69
	v_cndmask_b32_e64 v64, v64, 0, s[10:11]
	v_cndmask_b32_e64 v65, v65, 0, s[8:9]
	v_sub_f32_e32 v73, v196, v72
	v_cndmask_b32_e64 v69, v69, 0, s[12:13]
	v_add_f32_e32 v68, v69, v68
	v_add_f32_e32 v64, v64, v68
	v_add_f32_e32 v64, v65, v64
	v_sub_f32_e32 v65, v66, v72
	v_exp_f32_e32 v65, v65
	v_mov_b32_e32 v196, v72
	v_cndmask_b32_e64 v65, v65, 0, s[6:7]
	v_add_f32_e32 v64, v65, v64
	v_sub_f32_e32 v65, v67, v72
	v_exp_f32_e32 v65, v65
	s_nop 0
	v_cndmask_b32_e64 v65, v65, 0, vcc
	v_add_f32_e32 v64, v65, v64
	v_mov_b32_e32 v66, v64
	s_nop 1
	v_permlane16_swap_b32_e32 v66, v64
	v_exp_f32_e32 v65, v73
	s_waitcnt lgkmcnt(0)
	v_add_f32_e32 v64, v64, v66
	ds_bpermute_b32 v66, v88, v64
	s_waitcnt lgkmcnt(0)
	v_add_f32_e32 v64, v64, v66
	v_fmac_f32_e32 v64, v187, v65
	v_mov_b32_e32 v187, v64
	s_branch .LBB0_89

.LBB0_105:
	v_readfirstlane_b32 s11, v88
	v_readfirstlane_b32 s12, v144
	s_lshr_b32 s12, s12, 6
	s_cmp_lt_u32 s11, s12
	s_cbranch_scc1 .Lself_lazy
	v_mov_b32_e32 v64, v185
	v_mov_b32_e32 v65, v184
	v_mov_b32_e32 v66, v187
	v_mov_b32_e32 v67, v186
	s_nop 1
	v_permlane16_swap_b32_e32 v185, v64
	v_permlane16_swap_b32_e32 v184, v65
	v_permlane16_swap_b32_e32 v187, v66
	v_permlane16_swap_b32_e32 v186, v67
	v_add_f32_e32 v185, v185, v64
	v_add_f32_e32 v184, v184, v65
	v_add_f32_e32 v187, v187, v66
	v_add_f32_e32 v186, v186, v67
	v_mov_b32_e32 v64, v185
	v_mov_b32_e32 v65, v184
	v_mov_b32_e32 v66, v187
	v_mov_b32_e32 v67, v186
	s_nop 1
	v_permlane32_swap_b32_e32 v185, v64
	v_permlane32_swap_b32_e32 v184, v65
	v_permlane32_swap_b32_e32 v187, v66
	v_permlane32_swap_b32_e32 v186, v67
	v_add_f32_e32 v185, v185, v64
	v_add_f32_e32 v184, v184, v65
	v_add_f32_e32 v187, v187, v66
	v_add_f32_e32 v186, v186, v67
	v_add_u32_e32 v94, s10, v208
	v_add_u32_e32 v151, v94, v149
	ds_read_b128 v[76:79], v151
	v_add_u32_e32 v192, v147, v149
	ds_read_b128 v[64:67], v192 offset:32768
	ds_read_b128 v[84:87], v151 offset:2048
	v_add_u32_e32 v196, v94, v155
	v_add_u32_e32 v193, v147, v155
	ds_read_b128 v[72:75], v192 offset:40960
	ds_read_b128 v[132:135], v196
	ds_read_b128 v[128:131], v196 offset:2048
	ds_read_b128 v[80:83], v193 offset:32768
	ds_read_b128 v[68:71], v193 offset:40960
	s_waitcnt lgkmcnt(0)
	v_mfma_f32_16x16x32_bf16 v[96:99], v[76:79], v[64:67], 0
	v_lshl_or_b32 v194, v88, 6, v145
	v_lshrrev_b64 v[88:89], v88, v[172:173]
	v_and_b32_e32 v88, 1, v88
	v_mfma_f32_16x16x32_bf16 v[104:107], v[84:87], v[64:67], 0
	v_mov_b32_e32 v89, v153
	v_cmp_gt_i32_e64 s[8:9], v194, v144
	v_cmp_eq_u64_e32 vcc, 0, v[88:89]
	v_mfma_f32_16x16x32_bf16 v[96:99], v[132:135], v[80:83], v[96:99]
	s_or_b64 s[22:23], vcc, s[8:9]
	v_or_b32_e32 v95, 2, v194
	v_cmp_lt_i32_e64 s[20:21], v194, v144
	v_mfma_f32_16x16x32_bf16 v[104:107], v[128:131], v[80:83], v[104:107]
	v_cmp_gt_i32_e64 s[8:9], v95, v144
	s_nop 2
	v_cndmask_b32_e64 v89, v96, v204, s[22:23]
	v_or_b32_e32 v96, 3, v194
	v_cndmask_b32_e64 v92, v204, v97, s[20:21]
	s_or_b64 s[24:25], vcc, s[8:9]
	v_cmp_gt_i32_e64 s[8:9], v96, v144
	v_or_b32_e32 v97, 16, v194
	v_cndmask_b32_e64 v95, v98, v204, s[24:25]
	s_or_b64 s[26:27], vcc, s[8:9]
	v_cmp_gt_i32_e64 s[8:9], v97, v144
	v_or_b32_e32 v98, 17, v194
	v_cndmask_b32_e64 v96, v99, v204, s[26:27]
	s_or_b64 s[28:29], vcc, s[8:9]
	v_cmp_gt_i32_e64 s[8:9], v98, v144
	v_or_b32_e32 v99, 18, v194
	v_cndmask_b32_e32 v88, v92, v204, vcc
	v_cndmask_b32_e64 v97, v104, v204, s[28:29]
	s_or_b64 s[30:31], vcc, s[8:9]
	v_cmp_gt_i32_e64 s[8:9], v99, v144
	v_or_b32_e32 v104, 19, v194
	v_max3_f32 v92, v89, s75, v88
	s_or_b64 s[34:35], vcc, s[8:9]
	v_cmp_gt_i32_e64 s[8:9], v104, v144
	v_max3_f32 v92, v92, v95, v96
	v_cndmask_b32_e64 v98, v105, v204, s[30:31]
	s_or_b64 s[36:37], vcc, s[8:9]
	v_max3_f32 v92, v92, v97, v98
	v_cndmask_b32_e64 v99, v106, v204, s[34:35]
	v_cndmask_b32_e64 v116, v107, v204, s[36:37]
	v_add_u32_e32 v91, v94, v211
	v_max3_f32 v92, v92, v99, v116
	ds_read2st64_b64 v[100:103], v91 offset0:16 offset1:20
	v_mov_b32_e32 v104, v92
	s_nop 1
	v_permlane16_swap_b32_e32 v104, v92
	v_add_u32_e32 v93, s10, v209
	v_add_u32_e32 v90, v94, v210
	v_add_u32_e32 v105, v93, v210
	s_waitcnt lgkmcnt(0)
	v_mov_b32_e32 v122, v100
	s_waitcnt lgkmcnt(0)
	v_max_f32_e32 v100, v104, v104
	v_max_f32_e32 v92, v92, v100
	v_mov_b32_e32 v104, v92
	s_nop 1
	v_permlane32_swap_b32_e32 v104, v92
	v_add_u32_e32 v106, v93, v211
	ds_read2st64_b64 v[108:111], v90 offset0:16 offset1:20
	v_mov_b32_e32 v123, v101
	v_add_u32_e32 v225, v94, v213
	s_waitcnt lgkmcnt(1)
	v_max3_f32 v197, v223, v92, v104
	v_sub_f32_e32 v89, v89, v197
	v_exp_f32_e32 v89, v89
	v_sub_f32_e32 v88, v88, v197
	v_exp_f32_e32 v88, v88
	ds_read_b64 v[112:113], v90 offset:12288
	ds_read_b64 v[114:115], v91 offset:12288
	ds_read_b64 v[104:105], v105 offset:8192
	ds_read_b64 v[106:107], v106 offset:8192
	v_add_f32_e32 v91, 0, v89
	v_sub_f32_e32 v90, v223, v197
	v_add_f32_e32 v189, v88, v91
	v_sub_f32_e32 v91, v95, v197
	v_exp_f32_e32 v117, v91
	v_sub_f32_e32 v91, v96, v197
	v_exp_f32_e32 v190, v90
	v_exp_f32_e32 v119, v91
	v_sub_f32_e32 v91, v97, v197
	v_exp_f32_e32 v125, v91
	v_sub_f32_e32 v91, v98, v197
	v_exp_f32_e32 v127, v91
	v_sub_f32_e32 v91, v99, v197
	v_sub_f32_e32 v90, v116, v197
	s_waitcnt lgkmcnt(4)
	v_mov_b32_e32 v121, v109
	v_mov_b32_e32 v101, v111
	v_exp_f32_e32 v109, v91
	v_exp_f32_e32 v111, v90
	v_cvt_pk_bf16_f32 v92, v89, v88
	v_pk_mul_f32 v[90:91], v[58:59], v[190:191] op_sel_hi:[1,0]
	v_pk_mul_f32 v[88:89], v[56:57], v[190:191] op_sel_hi:[1,0]
	v_pk_mul_f32 v[58:59], v[50:51], v[190:191] op_sel_hi:[1,0]
	v_pk_mul_f32 v[56:57], v[48:49], v[190:191] op_sel_hi:[1,0]
	v_mfma_f32_16x16x32_bf16 v[48:51], v[76:79], v[72:75], 0
	v_mul_f32_e64 v98, v62, v190
	v_mul_f32_e64 v99, v63, v190
	v_pk_mul_f32 v[96:97], v[60:61], v[190:191] op_sel_hi:[1,0]
	v_pk_mul_f32 v[62:63], v[54:55], v[190:191] op_sel_hi:[1,0]
	v_pk_mul_f32 v[60:61], v[52:53], v[190:191] op_sel_hi:[1,0]
	v_mfma_f32_16x16x32_bf16 v[52:55], v[84:87], v[72:75], 0
	v_add_u32_e32 v223, v94, v212
	v_mov_b32_e32 v120, v108
	v_mov_b32_e32 v100, v110
	v_mfma_f32_16x16x32_bf16 v[48:51], v[132:135], v[68:71], v[48:51]
	v_add_u32_e32 v227, v93, v212
	v_add_u32_e32 v228, v93, v213
	v_or_b32_e32 v93, 32, v194
	v_mfma_f32_16x16x32_bf16 v[52:55], v[128:131], v[68:71], v[52:55]
	v_cmp_gt_i32_e64 s[10:11], v93, v144
	s_nop 2
	v_cndmask_b32_e64 v49, v204, v49, s[20:21]
	v_cndmask_b32_e64 v48, v48, v204, s[22:23]
	v_cndmask_b32_e32 v49, v49, v204, vcc
	v_max3_f32 v94, v48, s75, v49
	v_cndmask_b32_e64 v50, v50, v204, s[24:25]
	v_cndmask_b32_e64 v51, v51, v204, s[26:27]
	v_max3_f32 v94, v94, v50, v51
	v_cndmask_b32_e64 v108, v52, v204, s[28:29]
	v_cndmask_b32_e64 v110, v53, v204, s[30:31]
	v_max3_f32 v52, v94, v108, v110
	v_cndmask_b32_e64 v226, v54, v204, s[34:35]
	v_cndmask_b32_e64 v229, v55, v204, s[36:37]
	v_max3_f32 v52, v52, v226, v229
	v_mov_b32_e32 v53, v52
	s_nop 1
	v_permlane16_swap_b32_e32 v53, v52
	v_or_b32_e32 v93, 33, v194
	v_cmp_gt_i32_e64 s[8:9], v93, v144
	v_or_b32_e32 v93, 34, v194
	v_or_b32_e32 v54, 48, v194
	s_waitcnt lgkmcnt(0)
	v_max_f32_e32 v53, v53, v53
	v_max_f32_e32 v52, v52, v53
	v_mov_b32_e32 v53, v52
	s_nop 1
	v_permlane32_swap_b32_e32 v53, v52
	v_cmp_gt_i32_e64 s[12:13], v93, v144
	v_or_b32_e32 v93, 35, v194
	v_cmp_gt_i32_e64 s[14:15], v54, v144
	v_or_b32_e32 v54, 49, v194
	s_waitcnt lgkmcnt(0)
	v_max3_f32 v224, v222, v52, v53
	v_sub_f32_e32 v48, v48, v224
	v_exp_f32_e32 v232, v48
	v_sub_f32_e32 v48, v49, v224
	v_exp_f32_e32 v233, v48
	v_sub_f32_e32 v48, v50, v224
	v_exp_f32_e32 v116, v48
	v_add_f32_e32 v48, 0, v232
	v_add_f32_e32 v188, v233, v48
	v_sub_f32_e32 v48, v51, v224
	v_exp_f32_e32 v118, v48
	v_sub_f32_e32 v48, v108, v224
	v_exp_f32_e32 v124, v48
	v_pk_add_f32 v[52:53], v[116:117], v[188:189]
	v_cmp_gt_i32_e64 s[16:17], v93, v144
	v_cmp_gt_i32_e64 s[18:19], v54, v144
	v_cvt_pk_bf16_f32 v93, v117, v119
	v_cvt_pk_bf16_f32 v94, v125, v127
	v_cvt_pk_bf16_f32 v95, v109, v111
	v_sub_f32_e32 v54, v110, v224
	v_mfma_f32_16x16x32_bf16 v[48:51], v[120:123], v[92:95], v[96:99]
	v_exp_f32_e32 v126, v54
	v_or_b32_e32 v195, 50, v194
	v_cmp_gt_i32_e64 s[38:39], v195, v144
	v_pk_add_f32 v[96:97], v[118:119], v[52:53]
	v_mfma_f32_16x16x32_bf16 v[52:55], v[100:103], v[92:95], v[88:91]
	v_mov_b32_e32 v189, v190
	s_or_b64 s[10:11], vcc, s[10:11]
	s_or_b64 s[8:9], vcc, s[8:9]
	v_pk_add_f32 v[88:89], v[124:125], v[96:97]
	v_sub_f32_e32 v96, v226, v224
	v_exp_f32_e32 v108, v96
	ds_read_b128 v[96:99], v192 offset:49152
	v_pk_add_f32 v[230:231], v[126:127], v[88:89]
	v_mfma_f32_16x16x32_bf16 v[88:91], v[112:115], v[92:95], v[60:63]
	s_or_b64 s[12:13], vcc, s[12:13]
	s_or_b64 s[16:17], vcc, s[16:17]
	s_or_b64 s[14:15], vcc, s[14:15]
	v_sub_f32_e32 v60, v229, v224
	v_mfma_f32_16x16x32_bf16 v[92:95], v[104:107], v[92:95], v[56:59]
	v_cvt_pk_bf16_f32 v58, v124, v126
	ds_read_b128 v[124:127], v193 offset:49152
	v_exp_f32_e32 v110, v60
	v_cvt_pk_bf16_f32 v57, v116, v118
	v_pk_add_f32 v[60:61], v[108:109], v[230:231]
	v_sub_f32_e32 v56, v222, v224
	v_exp_f32_e32 v188, v56
	v_cvt_pk_bf16_f32 v56, v232, v233
	ds_read_b128 v[116:119], v192 offset:57344
	s_waitcnt lgkmcnt(2)
	v_mfma_f32_16x16x32_bf16 v[230:233], v[76:79], v[96:99], 0
	v_cvt_pk_bf16_f32 v59, v108, v110
	v_add_f32_e64 v60, v110, v60
	v_add_f32_e64 v61, v111, v61
	v_or_b32_e32 v222, 51, v194
	v_mfma_f32_16x16x32_bf16 v[234:237], v[84:87], v[96:99], 0
	ds_read_b128 v[108:111], v193 offset:57344
	v_pk_mul_f32 v[46:47], v[46:47], v[188:189] op_sel_hi:[1,0]
	v_pk_mul_f32 v[44:45], v[44:45], v[188:189] op_sel_hi:[1,0]
	s_waitcnt lgkmcnt(2)
	v_mfma_f32_16x16x32_bf16 v[192:195], v[132:135], v[124:127], v[230:233]
	v_mul_f32_e64 v30, v30, v188
	v_mul_f32_e64 v31, v31, v188
	v_pk_mul_f32 v[28:29], v[28:29], v[188:189] op_sel_hi:[1,0]
	v_pk_mul_f32 v[34:35], v[34:35], v[188:189] op_sel_hi:[1,0]
	v_mfma_f32_16x16x32_bf16 v[230:233], v[128:131], v[124:127], v[234:237]
	v_mul_f32_e64 v32, v32, v188
	v_mul_f32_e64 v33, v33, v188
	s_nop 0
	v_cndmask_b32_e64 v190, v192, v204, s[22:23]
	v_cndmask_b32_e64 v192, v204, v193, s[20:21]
	v_cndmask_b32_e32 v192, v192, v204, vcc
	v_max3_f32 v193, v190, s75, v192
	v_cndmask_b32_e64 v194, v194, v204, s[24:25]
	v_cndmask_b32_e64 v195, v195, v204, s[26:27]
	v_max3_f32 v193, v193, v194, v195
	v_cndmask_b32_e64 v226, v230, v204, s[28:29]
	v_cndmask_b32_e64 v230, v231, v204, s[30:31]
	v_max3_f32 v193, v193, v226, v230
	v_cndmask_b32_e64 v232, v232, v204, s[34:35]
	v_cndmask_b32_e64 v233, v233, v204, s[36:37]
	v_max3_f32 v193, v193, v232, v233
	v_mov_b32_e32 v229, v193
	s_nop 1
	v_permlane16_swap_b32_e32 v229, v193
	s_waitcnt lgkmcnt(1)
	v_mfma_f32_16x16x32_bf16 v[76:79], v[76:79], v[116:119], 0
	v_mul_f32_e64 v26, v26, v188
	v_mul_f32_e64 v27, v27, v188
	v_pk_mul_f32 v[24:25], v[24:25], v[188:189] op_sel_hi:[1,0]
	v_mov_b32_e32 v63, v61
	s_nop 1
	v_permlane16_swap_b32_e32 v63, v61
	s_waitcnt lgkmcnt(0)
	v_max_f32_e32 v229, v229, v229
	v_max_f32_e32 v193, v193, v229
	v_mov_b32_e32 v229, v193
	s_nop 1
	v_permlane32_swap_b32_e32 v229, v193
	v_mfma_f32_16x16x32_bf16 v[44:47], v[120:123], v[56:59], v[44:47]
	v_mov_b32_e32 v62, v60
	s_nop 1
	v_permlane16_swap_b32_e32 v62, v60
	s_or_b64 s[18:19], vcc, s[18:19]
	s_waitcnt lgkmcnt(0)
	v_max3_f32 v229, v191, v193, v229
	v_mfma_f32_16x16x32_bf16 v[28:31], v[100:103], v[56:59], v[28:31]
	v_sub_f32_e32 v190, v190, v229
	v_exp_f32_e32 v190, v190
	v_sub_f32_e32 v192, v192, v229
	v_mfma_f32_16x16x32_bf16 v[32:35], v[112:115], v[56:59], v[32:35]
	v_exp_f32_e32 v192, v192
	s_waitcnt lgkmcnt(0)
	v_pk_add_f32 v[60:61], v[60:61], v[62:63]
	v_mov_b32_e32 v63, v61
	s_nop 1
	v_permlane32_swap_b32_e32 v63, v61
	v_mfma_f32_16x16x32_bf16 v[24:27], v[104:107], v[56:59], v[24:27]
	v_sub_f32_e32 v58, v195, v229
	v_exp_f32_e32 v59, v58
	v_sub_f32_e32 v58, v226, v229
	v_mfma_f32_16x16x32_bf16 v[84:87], v[84:87], v[116:119], 0
	v_sub_f32_e32 v56, v191, v229
	v_exp_f32_e32 v191, v58
	v_sub_f32_e32 v58, v230, v229
	v_mfma_f32_16x16x32_bf16 v[76:79], v[132:135], v[108:111], v[76:79]
	v_exp_f32_e32 v193, v58
	v_sub_f32_e32 v58, v232, v229
	v_exp_f32_e32 v195, v58
	v_sub_f32_e32 v58, v233, v229
	v_mfma_f32_16x16x32_bf16 v[84:87], v[128:131], v[108:111], v[84:87]
	v_exp_f32_e32 v233, v58
	s_nop 1
	v_cndmask_b32_e64 v58, v204, v77, s[20:21]
	v_exp_f32_e32 v234, v56
	v_cndmask_b32_e64 v56, v76, v204, s[22:23]
	v_cndmask_b32_e32 v58, v58, v204, vcc
	v_max3_f32 v76, v56, s75, v58
	v_cndmask_b32_e64 v128, v78, v204, s[24:25]
	v_cndmask_b32_e64 v129, v79, v204, s[26:27]
	v_add_f32_e32 v57, 0, v190
	v_max3_f32 v76, v76, v128, v129
	v_cndmask_b32_e64 v130, v84, v204, s[28:29]
	v_cndmask_b32_e64 v131, v85, v204, s[30:31]
	v_add_f32_e32 v231, v192, v57
	v_sub_f32_e32 v57, v194, v229
	v_max3_f32 v76, v76, v130, v131
	v_cndmask_b32_e64 v194, v86, v204, s[34:35]
	v_cndmask_b32_e64 v232, v87, v204, s[36:37]
	v_max3_f32 v76, v76, v194, v232
	v_mov_b32_e32 v77, v76
	s_nop 1
	v_permlane16_swap_b32_e32 v77, v76
	v_pk_mul_f32 v[84:85], v[16:17], v[234:235] op_sel_hi:[1,0]
	v_pk_mul_f32 v[42:43], v[42:43], v[234:235] op_sel_hi:[1,0]
	v_pk_mul_f32 v[40:41], v[40:41], v[234:235] op_sel_hi:[1,0]
	v_pk_mul_f32 v[38:39], v[38:39], v[234:235] op_sel_hi:[1,0]
	s_waitcnt lgkmcnt(0)
	v_max_f32_e32 v77, v77, v77
	v_max_f32_e32 v133, v76, v77
	v_mov_b32_e32 v134, v133
	s_nop 1
	v_permlane32_swap_b32_e32 v134, v133
	v_pk_mul_f32 v[36:37], v[36:37], v[234:235] op_sel_hi:[1,0]
	v_pk_mul_f32 v[78:79], v[22:23], v[234:235] op_sel_hi:[1,0]
	v_pk_mul_f32 v[76:77], v[20:21], v[234:235] op_sel_hi:[1,0]
	v_pk_mul_f32 v[86:87], v[18:19], v[234:235] op_sel_hi:[1,0]
	s_waitcnt lgkmcnt(0)
	v_max3_f32 v226, v171, v133, v134
	v_sub_f32_e32 v16, v56, v226
	v_exp_f32_e32 v235, v16
	v_sub_f32_e32 v17, v58, v226
	v_exp_f32_e32 v236, v17
	v_sub_f32_e32 v17, v128, v226
	v_exp_f32_e32 v57, v57
	v_exp_f32_e32 v56, v17
	v_sub_f32_e32 v17, v129, v226
	v_exp_f32_e32 v58, v17
	v_sub_f32_e32 v17, v130, v226
	v_cvt_pk_bf16_f32 v132, v190, v192
	v_add_f32_e32 v16, 0, v235
	v_exp_f32_e32 v190, v17
	v_add_f32_e32 v230, v236, v16
	v_pk_add_f32 v[16:17], v[56:57], v[230:231]
	v_sub_f32_e32 v20, v131, v226
	v_pk_add_f32 v[16:17], v[58:59], v[16:17]
	v_cvt_pk_bf16_f32 v133, v57, v59
	v_cvt_pk_bf16_f32 v134, v191, v193
	v_cvt_pk_bf16_f32 v135, v195, v233
	v_exp_f32_e32 v192, v20
	v_pk_add_f32 v[128:129], v[190:191], v[16:17]
	v_mfma_f32_16x16x32_bf16 v[16:19], v[120:123], v[132:135], v[40:43]
	v_mov_b32_e32 v62, v60
	s_nop 1
	v_permlane32_swap_b32_e32 v62, v60
	v_cmp_gt_i32_e64 s[22:23], v222, v144
	s_or_b64 s[20:21], vcc, s[38:39]
	v_sub_f32_e32 v40, v194, v226
	v_mfma_f32_16x16x32_bf16 v[20:23], v[100:103], v[132:135], v[36:39]
	v_exp_f32_e32 v194, v40
	ds_read_b128 v[40:43], v151 offset:4096
	v_cvt_pk_bf16_f32 v38, v190, v192
	v_mfma_f32_16x16x32_bf16 v[76:79], v[112:115], v[132:135], v[76:79]
	v_sub_f32_e32 v36, v232, v226
	v_exp_f32_e32 v232, v36
	v_pk_add_f32 v[36:37], v[192:193], v[128:129]
	v_mov_b32_e32 v129, v234
	v_pk_add_f32 v[36:37], v[194:195], v[36:37]
	v_cvt_pk_bf16_f32 v39, v194, v232
	v_mfma_f32_16x16x32_bf16 v[84:87], v[104:107], v[132:135], v[84:87]
	v_add_f32_e64 v230, v232, v36
	v_add_f32_e64 v231, v233, v37
	v_sub_f32_e32 v36, v171, v226
	v_exp_f32_e32 v128, v36
	v_cvt_pk_bf16_f32 v36, v235, v236
	v_cvt_pk_bf16_f32 v37, v56, v58
	s_waitcnt lgkmcnt(1)
	v_pk_add_f32 v[130:131], v[60:61], v[62:63]
	v_pk_mul_f32 v[14:15], v[14:15], v[128:129] op_sel_hi:[1,0]
	v_pk_mul_f32 v[12:13], v[12:13], v[128:129] op_sel_hi:[1,0]
	v_pk_mul_f32 v[6:7], v[6:7], v[128:129] op_sel_hi:[1,0]
	v_pk_mul_f32 v[4:5], v[4:5], v[128:129] op_sel_hi:[1,0]
	v_mfma_f32_16x16x32_bf16 v[12:15], v[120:123], v[36:39], v[12:15]
	v_mov_b32_e32 v121, v231
	s_nop 1
	v_permlane16_swap_b32_e32 v121, v231
	v_mov_b32_e32 v120, v230
	s_nop 1
	v_permlane16_swap_b32_e32 v120, v230
	v_pk_mul_f32 v[10:11], v[10:11], v[128:129] op_sel_hi:[1,0]
	v_mfma_f32_16x16x32_bf16 v[4:7], v[112:115], v[36:39], v[4:7]
	ds_read_b128 v[112:115], v151 offset:6144
	v_pk_mul_f32 v[8:9], v[8:9], v[128:129] op_sel_hi:[1,0]
	v_pk_mul_f32 v[2:3], v[2:3], v[128:129] op_sel_hi:[1,0]
	v_pk_mul_f32 v[0:1], v[0:1], v[128:129] op_sel_hi:[1,0]
	v_mfma_f32_16x16x32_bf16 v[8:11], v[100:103], v[36:39], v[8:11]
	s_waitcnt lgkmcnt(1)
	v_pk_add_f32 v[132:133], v[230:231], v[120:121]
	ds_read_b128 v[120:123], v196 offset:6144
	s_or_b64 vcc, vcc, s[22:23]
	v_mfma_f32_16x16x32_bf16 v[0:3], v[104:107], v[36:39], v[0:3]
	ds_read_b128 v[36:39], v196 offset:4096
	ds_read2st64_b64 v[102:105], v223 offset0:16 offset1:20
	ds_bpermute_b32 v135, v159, v133
	v_mfma_f32_16x16x32_bf16 v[56:59], v[40:43], v[64:67], 0
	ds_bpermute_b32 v134, v159, v132
	s_waitcnt lgkmcnt(2)
	v_mov_b32_e32 v100, v102
	v_mfma_f32_16x16x32_bf16 v[60:63], v[112:115], v[64:67], 0
	ds_read2st64_b64 v[64:67], v225 offset0:16 offset1:20
	v_mov_b32_e32 v101, v103
	s_waitcnt lgkmcnt(0)
	v_mov_b32_e32 v102, v64
	v_mfma_f32_16x16x32_bf16 v[56:59], v[36:39], v[80:83], v[56:59]
	v_mov_b32_e32 v103, v65
	v_mov_b32_e32 v64, v104
	v_mov_b32_e32 v65, v105
	v_mfma_f32_16x16x32_bf16 v[60:63], v[120:123], v[80:83], v[60:63]
	ds_read_b64 v[104:105], v223 offset:12288
	ds_read_b64 v[106:107], v225 offset:12288
	ds_read_b64 v[80:81], v227 offset:8192
	ds_read_b64 v[82:83], v228 offset:8192
	v_cndmask_b32_e64 v56, v56, v204, s[10:11]
	v_cndmask_b32_e64 v151, v57, v204, s[8:9]
	v_max3_f32 v57, v56, s75, v151
	v_cndmask_b32_e64 v171, v58, v204, s[12:13]
	v_cndmask_b32_e64 v190, v59, v204, s[16:17]
	v_max3_f32 v57, v57, v171, v190
	v_cndmask_b32_e64 v192, v60, v204, s[14:15]
	v_cndmask_b32_e64 v194, v61, v204, s[18:19]
	v_max3_f32 v57, v57, v192, v194
	v_cndmask_b32_e64 v196, v62, v204, s[20:21]
	v_cndmask_b32_e32 v222, v63, v204, vcc
	v_max3_f32 v57, v57, v196, v222
	v_mov_b32_e32 v58, v57
	s_nop 1
	v_permlane16_swap_b32_e32 v58, v57
	s_waitcnt lgkmcnt(0)
	s_waitcnt vmcnt(0)
	s_barrier
	v_max_f32_e32 v58, v58, v58
	v_max_f32_e32 v57, v57, v58
	v_mov_b32_e32 v58, v57
	s_nop 1
	v_permlane32_swap_b32_e32 v58, v57
	s_waitcnt lgkmcnt(0)
	v_max3_f32 v223, v197, v57, v58
	v_sub_f32_e32 v56, v56, v223
	v_exp_f32_e32 v191, v56
	v_mfma_f32_16x16x32_bf16 v[56:59], v[40:43], v[72:75], 0
	v_sub_f32_e32 v60, v151, v223
	v_sub_f32_e32 v225, v197, v223
	v_exp_f32_e32 v197, v60
	v_mfma_f32_16x16x32_bf16 v[60:63], v[112:115], v[72:75], 0
	v_sub_f32_e32 v72, v190, v223
	v_exp_f32_e32 v73, v72
	v_sub_f32_e32 v72, v192, v223
	v_mfma_f32_16x16x32_bf16 v[56:59], v[36:39], v[68:71], v[56:59]
	v_exp_f32_e32 v193, v72
	v_sub_f32_e32 v72, v194, v223
	v_exp_f32_e32 v235, v72
	v_mfma_f32_16x16x32_bf16 v[60:63], v[120:123], v[68:71], v[60:63]
	v_sub_f32_e32 v70, v196, v223
	s_nop 2
	v_cndmask_b32_e64 v56, v56, v204, s[10:11]
	v_cndmask_b32_e64 v57, v57, v204, s[8:9]
	v_max3_f32 v68, v56, s75, v57
	v_cndmask_b32_e64 v58, v58, v204, s[12:13]
	v_cndmask_b32_e64 v59, v59, v204, s[16:17]
	v_max3_f32 v68, v68, v58, v59
	v_cndmask_b32_e64 v60, v60, v204, s[14:15]
	v_cndmask_b32_e64 v61, v61, v204, s[18:19]
	v_max3_f32 v68, v68, v60, v61
	v_cndmask_b32_e64 v62, v62, v204, s[20:21]
	v_cndmask_b32_e32 v63, v63, v204, vcc
	v_max3_f32 v68, v68, v62, v63
	v_mov_b32_e32 v69, v68
	s_nop 1
	v_permlane16_swap_b32_e32 v69, v68
	v_exp_f32_e32 v71, v70
	v_sub_f32_e32 v70, v222, v223
	v_sub_f32_e32 v151, v171, v223
	v_exp_f32_e32 v195, v151
	s_waitcnt lgkmcnt(0)
	v_max_f32_e32 v69, v69, v69
	v_max_f32_e32 v68, v68, v69
	v_mov_b32_e32 v72, v68
	s_nop 1
	v_permlane32_swap_b32_e32 v72, v68
	v_exp_f32_e32 v69, v225
	v_exp_f32_e32 v75, v70
	v_cvt_pk_bf16_f32 v230, v191, v197
	v_cvt_pk_bf16_f32 v231, v195, v73
	s_waitcnt lgkmcnt(0)
	v_max3_f32 v222, v224, v68, v72
	v_sub_f32_e32 v56, v56, v222
	v_exp_f32_e32 v190, v56
	v_sub_f32_e32 v56, v57, v222
	v_exp_f32_e32 v196, v56
	v_mov_b32_e32 v228, v69
	v_pk_add_f32 v[56:57], v[190:191], 0 op_sel_hi:[1,0]
	v_pk_mul_f32 v[50:51], v[50:51], v[228:229] op_sel_hi:[1,0]
	v_pk_add_f32 v[236:237], v[196:197], v[56:57]
	v_sub_f32_e32 v56, v58, v222
	v_exp_f32_e32 v194, v56
	v_sub_f32_e32 v56, v59, v222
	v_exp_f32_e32 v72, v56
	v_sub_f32_e32 v56, v60, v222
	v_exp_f32_e32 v192, v56
	v_sub_f32_e32 v56, v61, v222
	v_exp_f32_e32 v234, v56
	v_sub_f32_e32 v56, v62, v222
	v_pk_mul_f32 v[48:49], v[48:49], v[228:229] op_sel_hi:[1,0]
	v_cvt_pk_bf16_f32 v232, v193, v235
	v_cvt_pk_bf16_f32 v233, v71, v75
	v_exp_f32_e32 v70, v56
	v_sub_f32_e32 v56, v63, v222
	v_mfma_f32_16x16x32_bf16 v[60:63], v[100:103], v[230:233], v[48:51]
	v_exp_f32_e32 v74, v56
	v_sub_f32_e32 v68, v224, v222
	v_exp_f32_e32 v68, v68
	v_pk_mul_f32 v[50:51], v[54:55], v[228:229] op_sel_hi:[1,0]
	v_pk_mul_f32 v[48:49], v[52:53], v[228:229] op_sel_hi:[1,0]
	v_pk_mul_f32 v[46:47], v[46:47], v[68:69] op_sel_hi:[1,0]
	s_nop 0
	v_mfma_f32_16x16x32_bf16 v[56:59], v[64:67], v[230:233], v[48:51]
	v_mul_f32_e64 v44, v44, v68
	v_mul_f32_e64 v45, v45, v68
	v_pk_mul_f32 v[30:31], v[30:31], v[68:69] op_sel_hi:[1,0]
	v_pk_mul_f32 v[28:29], v[28:29], v[68:69] op_sel_hi:[1,0]
	v_pk_mul_f32 v[50:51], v[90:91], v[228:229] op_sel_hi:[1,0]
	v_pk_mul_f32 v[48:49], v[88:89], v[228:229] op_sel_hi:[1,0]
	v_cvt_pk_bf16_f32 v89, v194, v72
	v_cvt_pk_bf16_f32 v91, v70, v74
	v_cvt_pk_bf16_f32 v88, v190, v196
	v_pk_mul_f32 v[34:35], v[34:35], v[68:69] op_sel_hi:[1,0]
	v_pk_mul_f32 v[32:33], v[32:33], v[68:69] op_sel_hi:[1,0]
	v_mfma_f32_16x16x32_bf16 v[52:55], v[104:107], v[230:233], v[48:51]
	v_mul_f32_e64 v26, v26, v68
	v_mul_f32_e64 v27, v27, v68
	v_pk_mul_f32 v[24:25], v[24:25], v[68:69] op_sel_hi:[1,0]
	v_cvt_pk_bf16_f32 v90, v192, v234
	v_pk_mul_f32 v[48:49], v[92:93], v[228:229] op_sel_hi:[1,0]
	v_pk_add_f32 v[92:93], v[194:195], v[236:237]
	v_pk_mul_f32 v[50:51], v[94:95], v[228:229] op_sel_hi:[1,0]
	v_pk_add_f32 v[72:73], v[72:73], v[92:93]
	v_mfma_f32_16x16x32_bf16 v[92:95], v[40:43], v[96:99], 0
	v_add_f32_e64 v72, v192, v72
	v_add_f32_e64 v73, v193, v73
	v_pk_add_f32 v[72:73], v[234:235], v[72:73]
	v_mfma_f32_16x16x32_bf16 v[96:99], v[112:115], v[96:99], 0
	v_add_f32_e64 v70, v70, v72
	v_add_f32_e64 v71, v71, v73
	v_pk_fma_f32 v[72:73], v[184:185], v[188:189], v[130:131]
	v_pk_add_f32 v[74:75], v[74:75], v[70:71]
	v_mfma_f32_16x16x32_bf16 v[92:95], v[36:39], v[124:127], v[92:95]
	v_mov_b32_e32 v191, v75
	s_nop 1
	v_permlane16_swap_b32_e32 v191, v75
	ds_bpermute_b32 v190, v157, v74
	v_pk_add_f32 v[70:71], v[132:133], v[134:135]
	v_mfma_f32_16x16x32_bf16 v[96:99], v[120:123], v[124:127], v[96:99]
	v_fma_f32 v70, v186, v128, v70
	v_fma_f32 v71, v187, v129, v71
	s_nop 1
	v_cndmask_b32_e64 v92, v92, v204, s[10:11]
	v_cndmask_b32_e64 v93, v93, v204, s[8:9]
	v_max3_f32 v124, v92, s75, v93
	v_cndmask_b32_e64 v125, v94, v204, s[12:13]
	v_cndmask_b32_e64 v126, v95, v204, s[16:17]
	v_max3_f32 v94, v124, v125, v126
	v_cndmask_b32_e64 v124, v96, v204, s[14:15]
	v_cndmask_b32_e64 v127, v97, v204, s[18:19]
	v_max3_f32 v94, v94, v124, v127
	v_cndmask_b32_e64 v98, v98, v204, s[20:21]
	v_cndmask_b32_e32 v130, v99, v204, vcc
	v_max3_f32 v94, v94, v98, v130
	v_mov_b32_e32 v95, v94
	s_nop 1
	v_permlane16_swap_b32_e32 v95, v94
	v_mfma_f32_16x16x32_bf16 v[40:43], v[40:43], v[116:119], 0
	s_waitcnt lgkmcnt(0)
	v_pk_add_f32 v[74:75], v[74:75], v[190:191]
	ds_bpermute_b32 v129, v159, v75
	ds_bpermute_b32 v128, v159, v74
	s_waitcnt lgkmcnt(2)
	v_max_f32_e32 v95, v95, v95
	v_max_f32_e32 v94, v94, v95
	v_mov_b32_e32 v95, v94
	s_nop 1
	v_permlane32_swap_b32_e32 v95, v94
	v_mfma_f32_16x16x32_bf16 v[36:39], v[36:39], v[108:111], v[40:43]
	s_waitcnt lgkmcnt(0)
	v_pk_add_f32 v[74:75], v[74:75], v[128:129]
	s_waitcnt lgkmcnt(0)
	v_max3_f32 v191, v229, v94, v95
	v_mfma_f32_16x16x32_bf16 v[94:97], v[112:115], v[116:119], 0
	v_sub_f32_e32 v40, v126, v191
	v_exp_f32_e32 v99, v40
	s_nop 0
	v_cndmask_b32_e64 v36, v36, v204, s[10:11]
	v_mfma_f32_16x16x32_bf16 v[40:43], v[120:123], v[108:111], v[94:97]
	v_cndmask_b32_e64 v37, v37, v204, s[8:9]
	v_cndmask_b32_e64 v38, v38, v204, s[12:13]
	v_cndmask_b32_e64 v39, v39, v204, s[16:17]
	v_mfma_f32_16x16x32_bf16 v[44:47], v[100:103], v[88:91], v[44:47]
	v_fma_f32 v184, v72, v68, v74
	v_fma_f32 v185, v73, v69, v75
	s_nop 1
	v_cndmask_b32_e64 v40, v40, v204, s[14:15]
	v_cndmask_b32_e64 v41, v41, v204, s[18:19]
	v_mfma_f32_16x16x32_bf16 v[28:31], v[64:67], v[88:91], v[28:31]
	v_cndmask_b32_e64 v42, v42, v204, s[20:21]
	v_cndmask_b32_e32 v43, v43, v204, vcc
	s_andn2_b64 vcc, exec, s[4:5]
	v_mfma_f32_16x16x32_bf16 v[32:35], v[104:107], v[88:91], v[32:35]
	v_mfma_f32_16x16x32_bf16 v[24:27], v[80:83], v[88:91], v[24:27]
	v_sub_f32_e32 v89, v92, v191
	v_max3_f32 v92, v36, s75, v37
	v_max3_f32 v92, v92, v38, v39
	v_max3_f32 v92, v92, v40, v41
	v_max3_f32 v92, v92, v42, v43
	v_mov_b32_e32 v94, v92
	s_nop 1
	v_permlane16_swap_b32_e32 v94, v92
	v_sub_f32_e32 v90, v93, v191
	v_exp_f32_e32 v91, v90
	v_sub_f32_e32 v90, v125, v191
	v_exp_f32_e32 v93, v90
	s_waitcnt lgkmcnt(0)
	v_max_f32_e32 v94, v94, v94
	v_max_f32_e32 v92, v92, v94
	v_mov_b32_e32 v94, v92
	s_nop 1
	v_permlane32_swap_b32_e32 v94, v92
	v_sub_f32_e32 v90, v124, v191
	v_exp_f32_e32 v109, v90
	v_sub_f32_e32 v90, v127, v191
	v_sub_f32_e32 v88, v229, v191
	s_waitcnt lgkmcnt(0)
	v_max3_f32 v171, v226, v92, v94
	v_exp_f32_e32 v111, v90
	v_sub_f32_e32 v90, v98, v191
	v_sub_f32_e32 v36, v36, v171
	v_exp_f32_e32 v89, v89
	v_exp_f32_e32 v113, v90
	v_sub_f32_e32 v90, v130, v191
	v_exp_f32_e32 v117, v88
	v_exp_f32_e32 v88, v36
	v_sub_f32_e32 v36, v37, v171
	v_exp_f32_e32 v115, v90
	v_exp_f32_e32 v90, v36
	v_sub_f32_e32 v36, v38, v171
	v_exp_f32_e32 v92, v36
	v_sub_f32_e32 v36, v39, v171
	v_exp_f32_e32 v98, v36
	v_sub_f32_e32 v38, v40, v171
	v_pk_add_f32 v[36:37], v[88:89], 0 op_sel_hi:[1,0]
	v_exp_f32_e32 v108, v38
	v_sub_f32_e32 v38, v41, v171
	v_pk_add_f32 v[36:37], v[90:91], v[36:37]
	v_exp_f32_e32 v110, v38
	v_sub_f32_e32 v38, v42, v171
	v_pk_add_f32 v[36:37], v[92:93], v[36:37]
	v_exp_f32_e32 v112, v38
	v_sub_f32_e32 v38, v43, v171
	v_pk_add_f32 v[36:37], v[98:99], v[36:37]
	v_exp_f32_e32 v114, v38
	v_pk_add_f32 v[36:37], v[108:109], v[36:37]
	v_cvt_pk_bf16_f32 v94, v89, v91
	v_sub_f32_e32 v89, v226, v171
	v_pk_add_f32 v[36:37], v[110:111], v[36:37]
	v_mov_b32_e32 v122, v117
	v_pk_add_f32 v[36:37], v[112:113], v[36:37]
	v_exp_f32_e32 v116, v89
	v_pk_add_f32 v[36:37], v[114:115], v[36:37]
	v_mov_b32_e32 v39, v37
	s_nop 1
	v_permlane16_swap_b32_e32 v39, v37
	v_mov_b32_e32 v38, v36
	s_nop 1
	v_permlane16_swap_b32_e32 v38, v36
	v_pk_mul_f32 v[18:19], v[18:19], v[122:123] op_sel_hi:[1,0]
	v_pk_mul_f32 v[16:17], v[16:17], v[122:123] op_sel_hi:[1,0]
	v_cvt_pk_bf16_f32 v95, v93, v99
	v_cvt_pk_bf16_f32 v96, v109, v111
	s_waitcnt lgkmcnt(0)
	v_pk_add_f32 v[118:119], v[36:37], v[38:39]
	ds_bpermute_b32 v121, v159, v119
	ds_bpermute_b32 v120, v159, v118
	v_cvt_pk_bf16_f32 v97, v113, v115
	v_pk_mul_f32 v[14:15], v[14:15], v[116:117] op_sel_hi:[1,0]
	v_mfma_f32_16x16x32_bf16 v[40:43], v[100:103], v[94:97], v[16:19]
	v_mul_f32_e64 v12, v12, v116
	v_mul_f32_e64 v13, v13, v116
	v_pk_mul_f32 v[10:11], v[10:11], v[116:117] op_sel_hi:[1,0]
	v_pk_mul_f32 v[8:9], v[8:9], v[116:117] op_sel_hi:[1,0]
	v_pk_mul_f32 v[18:19], v[22:23], v[122:123] op_sel_hi:[1,0]
	v_pk_mul_f32 v[16:17], v[20:21], v[122:123] op_sel_hi:[1,0]
	v_pk_mul_f32 v[6:7], v[6:7], v[116:117] op_sel_hi:[1,0]
	v_pk_mul_f32 v[4:5], v[4:5], v[116:117] op_sel_hi:[1,0]
	v_mfma_f32_16x16x32_bf16 v[36:39], v[64:67], v[94:97], v[16:19]
	v_mul_f32_e64 v2, v2, v116
	v_mul_f32_e64 v3, v3, v116
	v_pk_mul_f32 v[0:1], v[0:1], v[116:117] op_sel_hi:[1,0]
	v_pk_mul_f32 v[18:19], v[78:79], v[122:123] op_sel_hi:[1,0]
	v_pk_mul_f32 v[16:17], v[76:77], v[122:123] op_sel_hi:[1,0]
	v_mfma_f32_16x16x32_bf16 v[48:51], v[80:83], v[230:233], v[48:51]
	v_cvt_pk_bf16_f32 v76, v88, v90
	v_cvt_pk_bf16_f32 v77, v92, v98
	v_cvt_pk_bf16_f32 v78, v108, v110
	v_cvt_pk_bf16_f32 v79, v112, v114
	s_nop 0
	v_mfma_f32_16x16x32_bf16 v[20:23], v[104:107], v[94:97], v[16:19]
	s_nop 2
	v_mul_f32_e64 v18, v86, v122
	v_mul_f32_e64 v19, v87, v122
	v_pk_mul_f32 v[16:17], v[84:85], v[122:123] op_sel_hi:[1,0]
	v_mfma_f32_16x16x32_bf16 v[12:15], v[100:103], v[76:79], v[12:15]
	s_nop 0
	v_mfma_f32_16x16x32_bf16 v[16:19], v[80:83], v[94:97], v[16:19]
	v_mfma_f32_16x16x32_bf16 v[8:11], v[64:67], v[76:79], v[8:11]
	s_waitcnt lgkmcnt(0)
	v_pk_add_f32 v[64:65], v[118:119], v[120:121]
	s_nop 0
	v_pk_fma_f32 v[186:187], v[70:71], v[116:117], v[64:65]
	v_mfma_f32_16x16x32_bf16 v[4:7], v[104:107], v[76:79], v[4:7]
	v_cndmask_b32_e64 v64, 0, 1, s[6:7]
	s_nop 0
	v_readfirstlane_b32 s6, v64
	v_mfma_f32_16x16x32_bf16 v[0:3], v[80:83], v[76:79], v[0:3]
	s_xor_b32 s42, s42, s6
	s_cbranch_vccz .LBB0_107

.LBB0_115:
	v_readfirstlane_b32 s11, v50
	v_readfirstlane_b32 s12, v144
	s_lshr_b32 s12, s12, 6
	s_add_u32 s13, s11, 7
	s_cmp_lt_u32 s11, s12
	s_cselect_b32 s14, 1, 0
	s_cmp_ge_u32 s13, s12
	s_cselect_b32 s15, 1, 0
	s_and_b32 s14, s14, s15
	s_cmp_lg_u32 s14, 0
	s_cbranch_scc1 .Lwinf_fast
	v_mov_b32_e32 v64, v133
	v_mov_b32_e32 v65, v132
	v_mov_b32_e32 v66, v165
	v_mov_b32_e32 v67, v164
	s_nop 1
	v_permlane16_swap_b32_e32 v133, v64
	v_permlane16_swap_b32_e32 v132, v65
	v_permlane16_swap_b32_e32 v165, v66
	v_permlane16_swap_b32_e32 v164, v67
	v_add_f32_e32 v133, v133, v64
	v_add_f32_e32 v132, v132, v65
	v_add_f32_e32 v165, v165, v66
	v_add_f32_e32 v164, v164, v67
	v_mov_b32_e32 v64, v133
	v_mov_b32_e32 v65, v132
	v_mov_b32_e32 v66, v165
	v_mov_b32_e32 v67, v164
	s_nop 1
	v_permlane32_swap_b32_e32 v133, v64
	v_permlane32_swap_b32_e32 v132, v65
	v_permlane32_swap_b32_e32 v165, v66
	v_permlane32_swap_b32_e32 v164, v67
	v_add_f32_e32 v133, v133, v64
	v_add_f32_e32 v132, v132, v65
	v_add_f32_e32 v165, v165, v66
	v_add_f32_e32 v164, v164, v67
	v_add_u32_e32 v120, s10, v208
	v_add_u32_e32 v189, v120, v149
	v_add_u32_e32 v190, v120, v155
	v_add_u32_e32 v52, v120, v210
	v_lshl_or_b32 v124, v50, 6, v145
	ds_read_b128 v[84:87], v189
	ds_read_b128 v[76:79], v190
	ds_read_b128 v[80:83], v189 offset:2048
	ds_read_b128 v[72:75], v190 offset:2048
	ds_read2st64_b64 v[48:51], v52 offset0:16 offset1:20
	v_add_u32_e32 v122, s10, v209
	v_add_u32_e32 v53, v120, v211
	ds_read2st64_b64 v[64:67], v53 offset0:16 offset1:20
	v_add_u32_e32 v174, v147, v149
	s_waitcnt lgkmcnt(0)
	v_mov_b32_e32 v68, v48
	v_add_u32_e32 v48, v122, v210
	ds_read_b64 v[60:61], v52 offset:12288
	ds_read_b64 v[62:63], v53 offset:12288
	ds_read_b64 v[56:57], v48 offset:8192
	ds_read_b128 v[52:55], v174 offset:32768
	v_add_u32_e32 v112, 0x200, v124
	v_cmp_le_i32_e32 vcc, v124, v144
	v_cmp_gt_i32_e64 s[8:9], v112, v144
	v_add_u32_e32 v112, 0x201, v124
	s_and_b64 s[22:23], vcc, s[8:9]
	v_cmp_lt_i32_e32 vcc, v124, v144
	v_cmp_gt_i32_e64 s[8:9], v112, v144
	v_or_b32_e32 v113, 2, v124
	v_add_u32_e32 v48, v122, v211
	v_add_u32_e32 v172, v147, v155
	s_and_b64 s[24:25], vcc, s[8:9]
	v_cmp_le_i32_e32 vcc, v113, v144
	v_add_u32_e32 v113, 0x202, v124
	v_mov_b32_e32 v69, v49
	v_mov_b32_e32 v70, v64
	v_mov_b32_e32 v71, v65
	v_mov_b32_e32 v64, v50
	v_mov_b32_e32 v65, v51
	ds_read_b64 v[58:59], v48 offset:8192
	ds_read_b128 v[48:51], v172 offset:32768
	v_cmp_gt_i32_e64 s[8:9], v113, v144
	v_or_b32_e32 v113, 3, v124
	s_waitcnt lgkmcnt(2)
	v_mfma_f32_16x16x32_bf16 v[104:107], v[84:87], v[52:55], 0
	s_and_b64 s[26:27], vcc, s[8:9]
	v_cmp_le_i32_e32 vcc, v113, v144
	v_add_u32_e32 v113, 0x203, v124
	v_cmp_gt_i32_e64 s[8:9], v113, v144
	v_or_b32_e32 v113, 16, v124
	v_mfma_f32_16x16x32_bf16 v[108:111], v[80:83], v[52:55], 0
	s_and_b64 s[28:29], vcc, s[8:9]
	v_cmp_le_i32_e32 vcc, v113, v144
	v_add_u32_e32 v113, 0x210, v124
	v_cmp_gt_i32_e64 s[8:9], v113, v144
	v_or_b32_e32 v113, 17, v124
	s_waitcnt lgkmcnt(0)
	v_mfma_f32_16x16x32_bf16 v[104:107], v[76:79], v[48:51], v[104:107]
	s_and_b64 s[30:31], vcc, s[8:9]
	v_cmp_le_i32_e32 vcc, v113, v144
	v_add_u32_e32 v113, 0x211, v124
	v_cmp_gt_i32_e64 s[8:9], v113, v144
	v_or_b32_e32 v113, 18, v124
	v_mfma_f32_16x16x32_bf16 v[108:111], v[72:75], v[48:51], v[108:111]
	s_and_b64 s[34:35], vcc, s[8:9]
	v_cmp_le_i32_e32 vcc, v113, v144
	v_add_u32_e32 v113, 0x212, v124
	v_cmp_gt_i32_e64 s[8:9], v113, v144
	v_or_b32_e32 v113, 19, v124
	v_cndmask_b32_e64 v104, v204, v104, s[22:23]
	v_cndmask_b32_e64 v105, v204, v105, s[24:25]
	s_and_b64 s[36:37], vcc, s[8:9]
	v_cmp_le_i32_e32 vcc, v113, v144
	v_add_u32_e32 v113, 0x213, v124
	v_max3_f32 v112, v104, s75, v105
	v_cndmask_b32_e64 v106, v204, v106, s[26:27]
	v_cndmask_b32_e64 v107, v204, v107, s[28:29]
	v_cmp_gt_i32_e64 s[8:9], v113, v144
	v_max3_f32 v112, v112, v106, v107
	v_cndmask_b32_e64 v108, v204, v108, s[30:31]
	v_cndmask_b32_e64 v109, v204, v109, s[34:35]
	s_and_b64 s[38:39], vcc, s[8:9]
	v_max3_f32 v112, v112, v108, v109
	v_cndmask_b32_e64 v110, v204, v110, s[36:37]
	v_cndmask_b32_e64 v111, v204, v111, s[38:39]
	v_max3_f32 v112, v112, v110, v111
	v_mov_b32_e32 v113, v112
	s_nop 1
	v_permlane16_swap_b32_e32 v113, v112
	v_add_u32_e32 v191, v120, v212
	v_add_u32_e32 v192, v120, v213
	v_add_u32_e32 v193, v122, v212
	v_add_u32_e32 v194, v122, v213
	s_waitcnt lgkmcnt(0)
	v_max_f32_e32 v113, v113, v113
	v_max_f32_e32 v112, v112, v113
	v_mov_b32_e32 v113, v112
	s_nop 1
	v_permlane32_swap_b32_e32 v113, v112
	s_waitcnt lgkmcnt(0)
	v_max3_f32 v151, v184, v112, v113
	v_sub_f32_e32 v112, v184, v151
	v_exp_f32_e32 v134, v112
	v_sub_f32_e32 v104, v104, v151
	v_exp_f32_e32 v104, v104
	v_sub_f32_e32 v105, v105, v151
	v_pk_mul_f32 v[116:117], v[100:101], v[134:135] op_sel_hi:[1,0]
	v_pk_mul_f32 v[100:101], v[88:89], v[134:135] op_sel_hi:[1,0]
	v_or_b32_e32 v88, 32, v124
	v_cmp_le_i32_e32 vcc, v88, v144
	v_add_u32_e32 v88, 0x220, v124
	v_cmp_gt_i32_e64 s[8:9], v88, v144
	v_or_b32_e32 v88, 33, v124
	s_and_b64 vcc, vcc, s[8:9]
	v_cmp_le_i32_e64 s[8:9], v88, v144
	v_add_u32_e32 v88, 0x221, v124
	v_cmp_gt_i32_e64 s[10:11], v88, v144
	v_or_b32_e32 v88, 34, v124
	s_and_b64 s[8:9], s[8:9], s[10:11]
	v_cmp_le_i32_e64 s[10:11], v88, v144
	v_add_u32_e32 v88, 0x222, v124
	v_cmp_gt_i32_e64 s[12:13], v88, v144
	v_or_b32_e32 v88, 35, v124
	s_and_b64 s[10:11], s[10:11], s[12:13]
	v_cmp_le_i32_e64 s[12:13], v88, v144
	v_add_u32_e32 v88, 0x223, v124
	v_cmp_gt_i32_e64 s[14:15], v88, v144
	v_or_b32_e32 v88, 48, v124
	s_and_b64 s[12:13], s[12:13], s[14:15]
	v_cmp_le_i32_e64 s[14:15], v88, v144
	v_add_u32_e32 v88, 0x230, v124
	v_cmp_gt_i32_e64 s[16:17], v88, v144
	v_or_b32_e32 v88, 49, v124
	s_and_b64 s[14:15], s[14:15], s[16:17]
	v_cmp_le_i32_e64 s[16:17], v88, v144
	v_add_u32_e32 v88, 0x231, v124
	v_exp_f32_e32 v105, v105
	v_cmp_gt_i32_e64 s[18:19], v88, v144
	v_or_b32_e32 v88, 50, v124
	s_and_b64 s[16:17], s[16:17], s[18:19]
	v_cmp_le_i32_e64 s[18:19], v88, v144
	v_add_u32_e32 v88, 0x232, v124
	v_cmp_gt_i32_e64 s[20:21], v88, v144
	v_or_b32_e32 v88, 51, v124
	v_add_f32_e32 v113, 0, v104
	v_sub_f32_e32 v106, v106, v151
	s_and_b64 s[18:19], s[18:19], s[20:21]
	v_cmp_le_i32_e64 s[20:21], v88, v144
	v_add_u32_e32 v88, 0x233, v124
	v_add_f32_e32 v167, v105, v113
	v_exp_f32_e32 v121, v106
	v_sub_f32_e32 v106, v107, v151
	v_pk_mul_f32 v[118:119], v[102:103], v[134:135] op_sel_hi:[1,0]
	v_pk_mul_f32 v[114:115], v[94:95], v[134:135] op_sel_hi:[1,0]
	v_pk_mul_f32 v[112:113], v[92:93], v[134:135] op_sel_hi:[1,0]
	v_pk_mul_f32 v[102:103], v[90:91], v[134:135] op_sel_hi:[1,0]
	v_cmp_gt_i32_e64 s[42:43], v88, v144
	ds_read_b128 v[92:95], v174 offset:40960
	ds_read_b128 v[88:91], v172 offset:40960
	v_exp_f32_e32 v123, v106
	v_sub_f32_e32 v106, v108, v151
	v_exp_f32_e32 v125, v106
	v_sub_f32_e32 v106, v109, v151
	v_exp_f32_e32 v127, v106
	v_sub_f32_e32 v106, v110, v151
	v_exp_f32_e32 v129, v106
	v_sub_f32_e32 v106, v111, v151
	v_pk_mul_f32 v[110:111], v[98:99], v[134:135] op_sel_hi:[1,0]
	v_pk_mul_f32 v[108:109], v[96:97], v[134:135] op_sel_hi:[1,0]
	s_waitcnt lgkmcnt(1)
	v_mfma_f32_16x16x32_bf16 v[96:99], v[84:87], v[92:95], 0
	v_exp_f32_e32 v131, v106
	v_cvt_pk_bf16_f32 v104, v104, v105
	v_cvt_pk_bf16_f32 v105, v121, v123
	v_mfma_f32_16x16x32_bf16 v[176:179], v[80:83], v[92:95], 0
	v_cvt_pk_bf16_f32 v106, v125, v127
	v_cvt_pk_bf16_f32 v107, v129, v131
	s_and_b64 s[20:21], s[20:21], s[42:43]
	s_waitcnt lgkmcnt(0)
	v_mfma_f32_16x16x32_bf16 v[96:99], v[76:79], v[88:91], v[96:99]
	v_mfma_f32_16x16x32_bf16 v[176:179], v[72:75], v[88:91], v[176:179]
	v_mfma_f32_16x16x32_bf16 v[108:111], v[64:67], v[104:107], v[108:111]
	s_nop 5
	v_cndmask_b32_e64 v96, v204, v96, s[22:23]
	v_cndmask_b32_e64 v97, v204, v97, s[24:25]
	v_max3_f32 v120, v96, s75, v97
	v_cndmask_b32_e64 v98, v204, v98, s[26:27]
	v_cndmask_b32_e64 v99, v204, v99, s[28:29]
	v_max3_f32 v120, v120, v98, v99
	v_cndmask_b32_e64 v124, v204, v176, s[30:31]
	v_cndmask_b32_e64 v126, v204, v177, s[34:35]
	v_max3_f32 v120, v120, v124, v126
	v_cndmask_b32_e64 v128, v204, v178, s[36:37]
	v_cndmask_b32_e64 v130, v204, v179, s[38:39]
	v_max3_f32 v120, v120, v128, v130
	v_mov_b32_e32 v122, v120
	s_nop 1
	v_permlane16_swap_b32_e32 v122, v120
	v_mfma_f32_16x16x32_bf16 v[112:115], v[60:63], v[104:107], v[112:115]
	s_waitcnt lgkmcnt(0)
	v_max_f32_e32 v122, v122, v122
	v_max_f32_e32 v120, v120, v122
	v_mov_b32_e32 v122, v120
	s_nop 1
	v_permlane32_swap_b32_e32 v122, v120
	s_waitcnt lgkmcnt(0)
	v_max3_f32 v195, v182, v120, v122
	v_sub_f32_e32 v96, v96, v195
	v_exp_f32_e32 v135, v96
	v_sub_f32_e32 v97, v97, v195
	v_exp_f32_e32 v171, v97
	v_add_f32_e32 v96, 0, v135
	v_add_f32_e32 v166, v171, v96
	v_sub_f32_e32 v96, v98, v195
	v_exp_f32_e32 v120, v96
	v_sub_f32_e32 v98, v99, v195
	v_exp_f32_e32 v122, v98
	v_sub_f32_e32 v98, v124, v195
	v_exp_f32_e32 v124, v98
	v_sub_f32_e32 v98, v126, v195
	v_exp_f32_e32 v126, v98
	v_sub_f32_e32 v98, v128, v195
	v_pk_add_f32 v[96:97], v[120:121], v[166:167]
	v_exp_f32_e32 v128, v98
	v_sub_f32_e32 v98, v130, v195
	v_pk_add_f32 v[96:97], v[122:123], v[96:97]
	v_exp_f32_e32 v130, v98
	v_pk_add_f32 v[96:97], v[124:125], v[96:97]
	s_nop 0
	v_pk_add_f32 v[96:97], v[126:127], v[96:97]
	s_nop 0
	v_pk_add_f32 v[96:97], v[128:129], v[96:97]
	s_nop 0
	v_pk_add_f32 v[96:97], v[130:131], v[96:97]
	v_mov_b32_e32 v99, v97
	s_nop 1
	v_permlane16_swap_b32_e32 v99, v97
	v_mov_b32_e32 v98, v96
	s_nop 1
	v_permlane16_swap_b32_e32 v98, v96
	s_waitcnt lgkmcnt(0)
	v_pk_add_f32 v[166:167], v[96:97], v[98:99]
	v_mov_b32_e32 v177, v167
	s_nop 1
	v_permlane32_swap_b32_e32 v177, v167
	v_mov_b32_e32 v176, v166
	s_nop 1
	v_permlane32_swap_b32_e32 v176, v166
	v_mfma_f32_16x16x32_bf16 v[96:99], v[68:71], v[104:107], v[116:119]
	v_mfma_f32_16x16x32_bf16 v[116:119], v[56:59], v[104:107], v[100:103]
	v_mov_b32_e32 v105, v134
	v_cvt_pk_bf16_f32 v102, v124, v126
	v_cvt_pk_bf16_f32 v103, v128, v130
	s_nop 1
	v_sub_f32_e32 v100, v182, v195
	v_exp_f32_e32 v104, v100
	s_waitcnt lgkmcnt(0)
	v_pk_add_f32 v[100:101], v[166:167], v[176:177]
	v_pk_mul_f32 v[38:39], v[38:39], v[104:105] op_sel_hi:[1,0]
	v_pk_fma_f32 v[166:167], v[132:133], v[104:105], v[100:101]
	v_cvt_pk_bf16_f32 v101, v120, v122
	v_pk_mul_f32 v[36:37], v[36:37], v[104:105] op_sel_hi:[1,0]
	v_pk_mul_f32 v[34:35], v[34:35], v[104:105] op_sel_hi:[1,0]
	v_pk_mul_f32 v[32:33], v[32:33], v[104:105] op_sel_hi:[1,0]
	v_pk_mul_f32 v[30:31], v[30:31], v[104:105] op_sel_hi:[1,0]
	v_pk_mul_f32 v[28:29], v[28:29], v[104:105] op_sel_hi:[1,0]
	v_pk_mul_f32 v[26:27], v[26:27], v[104:105] op_sel_hi:[1,0]
	v_pk_mul_f32 v[24:25], v[24:25], v[104:105] op_sel_hi:[1,0]
	ds_read_b128 v[120:123], v174 offset:49152
	ds_read_b128 v[104:107], v172 offset:49152
	v_cvt_pk_bf16_f32 v100, v135, v171
	s_waitcnt lgkmcnt(1)
	v_mfma_f32_16x16x32_bf16 v[124:127], v[80:83], v[120:123], 0
	v_mfma_f32_16x16x32_bf16 v[36:39], v[68:71], v[100:103], v[36:39]
	v_mfma_f32_16x16x32_bf16 v[32:35], v[64:67], v[100:103], v[32:35]
	v_mfma_f32_16x16x32_bf16 v[28:31], v[60:63], v[100:103], v[28:31]
	v_mfma_f32_16x16x32_bf16 v[24:27], v[56:59], v[100:103], v[24:27]
	v_mfma_f32_16x16x32_bf16 v[100:103], v[84:87], v[120:123], 0
	s_waitcnt lgkmcnt(0)
	v_mfma_f32_16x16x32_bf16 v[100:103], v[76:79], v[104:107], v[100:103]
	v_mfma_f32_16x16x32_bf16 v[124:127], v[72:75], v[104:107], v[124:127]
	s_nop 6
	v_cndmask_b32_e64 v100, v204, v100, s[22:23]
	v_cndmask_b32_e64 v101, v204, v101, s[24:25]
	v_max3_f32 v128, v100, s75, v101
	v_cndmask_b32_e64 v102, v204, v102, s[26:27]
	v_cndmask_b32_e64 v103, v204, v103, s[28:29]
	v_max3_f32 v128, v128, v102, v103
	v_cndmask_b32_e64 v124, v204, v124, s[30:31]
	v_cndmask_b32_e64 v125, v204, v125, s[34:35]
	v_max3_f32 v128, v128, v124, v125
	v_cndmask_b32_e64 v126, v204, v126, s[36:37]
	v_cndmask_b32_e64 v127, v204, v127, s[38:39]
	v_max3_f32 v128, v128, v126, v127
	v_mov_b32_e32 v129, v128
	s_nop 1
	v_permlane16_swap_b32_e32 v129, v128
	s_waitcnt lgkmcnt(0)
	v_max_f32_e32 v129, v129, v129
	v_max_f32_e32 v128, v128, v129
	v_mov_b32_e32 v129, v128
	s_nop 1
	v_permlane32_swap_b32_e32 v129, v128
	s_waitcnt lgkmcnt(0)
	v_max3_f32 v196, v170, v128, v129
	v_sub_f32_e32 v128, v170, v196
	v_sub_f32_e32 v102, v102, v196
	v_exp_f32_e32 v171, v102
	v_sub_f32_e32 v102, v103, v196
	v_exp_f32_e32 v182, v128
	v_exp_f32_e32 v173, v102
	v_sub_f32_e32 v102, v124, v196
	v_sub_f32_e32 v100, v100, v196
	v_exp_f32_e32 v175, v102
	v_sub_f32_e32 v102, v125, v196
	v_exp_f32_e32 v100, v100
	v_sub_f32_e32 v101, v101, v196
	v_exp_f32_e32 v177, v102
	v_sub_f32_e32 v102, v126, v196
	v_exp_f32_e32 v101, v101
	v_exp_f32_e32 v179, v102
	v_sub_f32_e32 v102, v127, v196
	v_pk_mul_f32 v[134:135], v[46:47], v[182:183] op_sel_hi:[1,0]
	v_pk_mul_f32 v[132:133], v[44:45], v[182:183] op_sel_hi:[1,0]
	v_pk_mul_f32 v[126:127], v[22:23], v[182:183] op_sel_hi:[1,0]
	v_pk_mul_f32 v[124:125], v[20:21], v[182:183] op_sel_hi:[1,0]
	v_pk_mul_f32 v[46:47], v[18:19], v[182:183] op_sel_hi:[1,0]
	v_pk_mul_f32 v[44:45], v[16:17], v[182:183] op_sel_hi:[1,0]
	ds_read_b128 v[20:23], v174 offset:57344
	ds_read_b128 v[16:19], v172 offset:57344
	v_add_f32_e32 v129, 0, v100
	v_add_f32_e32 v185, v101, v129
	v_pk_mul_f32 v[130:131], v[42:43], v[182:183] op_sel_hi:[1,0]
	v_pk_mul_f32 v[128:129], v[40:41], v[182:183] op_sel_hi:[1,0]
	s_waitcnt lgkmcnt(1)
	v_mfma_f32_16x16x32_bf16 v[40:43], v[84:87], v[20:23], 0
	v_exp_f32_e32 v181, v102
	v_cvt_pk_bf16_f32 v100, v100, v101
	v_cvt_pk_bf16_f32 v101, v171, v173
	v_mfma_f32_16x16x32_bf16 v[80:83], v[80:83], v[20:23], 0
	v_cvt_pk_bf16_f32 v102, v175, v177
	v_cvt_pk_bf16_f32 v103, v179, v181
	s_waitcnt lgkmcnt(0)
	v_mfma_f32_16x16x32_bf16 v[40:43], v[76:79], v[16:19], v[40:43]
	v_mfma_f32_16x16x32_bf16 v[72:75], v[72:75], v[16:19], v[80:83]
	v_mfma_f32_16x16x32_bf16 v[80:83], v[56:59], v[100:103], v[44:47]
	s_nop 5
	v_cndmask_b32_e64 v40, v204, v40, s[22:23]
	v_cndmask_b32_e64 v41, v204, v41, s[24:25]
	v_max3_f32 v76, v40, s75, v41
	v_cndmask_b32_e64 v42, v204, v42, s[26:27]
	v_cndmask_b32_e64 v43, v204, v43, s[28:29]
	v_max3_f32 v76, v76, v42, v43
	v_cndmask_b32_e64 v72, v204, v72, s[30:31]
	v_cndmask_b32_e64 v73, v204, v73, s[34:35]
	v_max3_f32 v76, v76, v72, v73
	v_cndmask_b32_e64 v74, v204, v74, s[36:37]
	v_cndmask_b32_e64 v75, v204, v75, s[38:39]
	v_max3_f32 v76, v76, v74, v75
	v_mov_b32_e32 v77, v76
	s_nop 1
	v_permlane16_swap_b32_e32 v77, v76
	s_waitcnt lgkmcnt(0)
	v_max_f32_e32 v77, v77, v77
	v_max_f32_e32 v76, v76, v77
	v_mov_b32_e32 v77, v76
	s_nop 1
	v_permlane32_swap_b32_e32 v77, v76
	s_waitcnt lgkmcnt(0)
	v_max3_f32 v197, v188, v76, v77
	v_sub_f32_e32 v40, v40, v197
	v_exp_f32_e32 v214, v40
	v_sub_f32_e32 v41, v41, v197
	v_exp_f32_e32 v215, v41
	v_sub_f32_e32 v44, v188, v197
	v_add_f32_e32 v40, 0, v214
	v_mfma_f32_16x16x32_bf16 v[76:79], v[60:63], v[100:103], v[124:127]
	v_add_f32_e32 v184, v215, v40
	v_sub_f32_e32 v40, v42, v197
	v_exp_f32_e32 v170, v40
	v_sub_f32_e32 v42, v43, v197
	v_exp_f32_e32 v172, v42
	v_sub_f32_e32 v42, v72, v197
	v_exp_f32_e32 v174, v42
	v_sub_f32_e32 v42, v73, v197
	v_exp_f32_e32 v176, v42
	v_sub_f32_e32 v42, v74, v197
	v_pk_add_f32 v[40:41], v[170:171], v[184:185]
	v_exp_f32_e32 v178, v42
	v_sub_f32_e32 v42, v75, v197
	v_pk_add_f32 v[40:41], v[172:173], v[40:41]
	v_exp_f32_e32 v180, v42
	v_pk_add_f32 v[40:41], v[174:175], v[40:41]
	v_mfma_f32_16x16x32_bf16 v[72:75], v[64:67], v[100:103], v[128:131]
	v_add_f32_e64 v40, v176, v40
	v_add_f32_e64 v41, v177, v41
	v_cvt_pk_bf16_f32 v46, v174, v176
	v_cvt_pk_bf16_f32 v47, v178, v180
	v_pk_add_f32 v[40:41], v[178:179], v[40:41]
	s_nop 0
	v_pk_add_f32 v[40:41], v[180:181], v[40:41]
	v_mov_b32_e32 v43, v41
	s_nop 1
	v_permlane16_swap_b32_e32 v43, v41
	v_mov_b32_e32 v42, v40
	s_nop 1
	v_permlane16_swap_b32_e32 v42, v40
	s_waitcnt lgkmcnt(0)
	v_pk_add_f32 v[84:85], v[40:41], v[42:43]
	v_mov_b32_e32 v87, v85
	s_nop 1
	v_permlane32_swap_b32_e32 v87, v85
	v_mov_b32_e32 v86, v84
	s_nop 1
	v_permlane32_swap_b32_e32 v86, v84
	v_mfma_f32_16x16x32_bf16 v[40:43], v[68:71], v[100:103], v[132:135]
	v_exp_f32_e32 v100, v44
	v_mov_b32_e32 v101, v182
	s_waitcnt lgkmcnt(0)
	v_pk_add_f32 v[44:45], v[84:85], v[86:87]
	s_nop 0
	v_pk_fma_f32 v[134:135], v[164:165], v[100:101], v[44:45]
	v_cvt_pk_bf16_f32 v44, v214, v215
	v_cvt_pk_bf16_f32 v45, v170, v172
	v_pk_mul_f32 v[14:15], v[14:15], v[100:101] op_sel_hi:[1,0]
	v_pk_mul_f32 v[12:13], v[12:13], v[100:101] op_sel_hi:[1,0]
	v_pk_mul_f32 v[10:11], v[10:11], v[100:101] op_sel_hi:[1,0]
	v_pk_mul_f32 v[8:9], v[8:9], v[100:101] op_sel_hi:[1,0]
	v_pk_mul_f32 v[6:7], v[6:7], v[100:101] op_sel_hi:[1,0]
	v_pk_mul_f32 v[4:5], v[4:5], v[100:101] op_sel_hi:[1,0]
	v_pk_mul_f32 v[2:3], v[2:3], v[100:101] op_sel_hi:[1,0]
	v_pk_mul_f32 v[0:1], v[0:1], v[100:101] op_sel_hi:[1,0]
	v_mfma_f32_16x16x32_bf16 v[12:15], v[68:71], v[44:47], v[12:15]
	v_mfma_f32_16x16x32_bf16 v[8:11], v[64:67], v[44:47], v[8:11]
	v_mfma_f32_16x16x32_bf16 v[4:7], v[60:63], v[44:47], v[4:7]
	v_mfma_f32_16x16x32_bf16 v[0:3], v[56:59], v[44:47], v[0:3]
	ds_read_b128 v[124:127], v189 offset:4096
	ds_read_b128 v[44:47], v190 offset:4096
	ds_read_b128 v[128:131], v189 offset:6144
	ds_read_b128 v[84:87], v190 offset:6144
	ds_read2st64_b64 v[56:59], v191 offset0:16 offset1:20
	ds_read2st64_b64 v[64:67], v192 offset0:16 offset1:20
	s_waitcnt lgkmcnt(1)
	v_mov_b32_e32 v68, v56
	v_mfma_f32_16x16x32_bf16 v[100:103], v[124:127], v[52:55], 0
	v_mov_b32_e32 v69, v57
	s_waitcnt lgkmcnt(0)
	v_mov_b32_e32 v70, v64
	v_mov_b32_e32 v71, v65
	v_mfma_f32_16x16x32_bf16 v[52:55], v[128:131], v[52:55], 0
	v_mov_b32_e32 v64, v58
	v_mov_b32_e32 v65, v59
	ds_read_b64 v[60:61], v191 offset:12288
	ds_read_b64 v[62:63], v192 offset:12288
	ds_read_b64 v[56:57], v193 offset:8192
	ds_read_b64 v[58:59], v194 offset:8192
	v_mfma_f32_16x16x32_bf16 v[100:103], v[44:47], v[48:51], v[100:103]
	s_waitcnt lgkmcnt(0)
	s_waitcnt vmcnt(0)
	s_barrier
	v_mfma_f32_16x16x32_bf16 v[48:51], v[84:87], v[48:51], v[52:55]
	s_nop 4
	v_cndmask_b32_e32 v52, v204, v100, vcc
	v_cndmask_b32_e64 v53, v204, v101, s[8:9]
	v_max3_f32 v54, v52, s75, v53
	v_cndmask_b32_e64 v100, v204, v102, s[10:11]
	v_cndmask_b32_e64 v101, v204, v103, s[12:13]
	v_max3_f32 v54, v54, v100, v101
	v_cndmask_b32_e64 v48, v204, v48, s[14:15]
	v_cndmask_b32_e64 v49, v204, v49, s[16:17]
	v_max3_f32 v54, v54, v48, v49
	v_cndmask_b32_e64 v50, v204, v50, s[18:19]
	v_cndmask_b32_e64 v51, v204, v51, s[20:21]
	v_max3_f32 v54, v54, v50, v51
	v_mov_b32_e32 v55, v54
	s_nop 1
	v_permlane16_swap_b32_e32 v55, v54
	s_waitcnt lgkmcnt(0)
	v_max_f32_e32 v55, v55, v55
	v_max_f32_e32 v54, v54, v55
	v_mov_b32_e32 v55, v54
	s_nop 1
	v_permlane32_swap_b32_e32 v55, v54
	s_waitcnt lgkmcnt(0)
	v_max3_f32 v184, v151, v54, v55
	v_sub_f32_e32 v52, v52, v184
	v_exp_f32_e32 v55, v52
	v_sub_f32_e32 v52, v53, v184
	v_exp_f32_e32 v165, v52
	v_sub_f32_e32 v52, v100, v184
	v_exp_f32_e32 v171, v52
	v_sub_f32_e32 v52, v101, v184
	v_mfma_f32_16x16x32_bf16 v[100:103], v[124:127], v[92:95], 0
	v_sub_f32_e32 v54, v151, v184
	v_exp_f32_e32 v173, v52
	v_exp_f32_e32 v53, v54
	v_mfma_f32_16x16x32_bf16 v[92:95], v[128:131], v[92:95], 0
	v_sub_f32_e32 v48, v48, v184
	v_exp_f32_e32 v175, v48
	v_sub_f32_e32 v48, v49, v184
	v_mfma_f32_16x16x32_bf16 v[100:103], v[44:47], v[88:91], v[100:103]
	v_exp_f32_e32 v177, v48
	v_sub_f32_e32 v48, v50, v184
	v_exp_f32_e32 v179, v48
	v_mfma_f32_16x16x32_bf16 v[88:91], v[84:87], v[88:91], v[92:95]
	v_sub_f32_e32 v48, v51, v184
	s_nop 2
	v_cndmask_b32_e32 v52, v204, v100, vcc
	v_exp_f32_e32 v181, v48
	v_cndmask_b32_e64 v92, v204, v101, s[8:9]
	v_max3_f32 v54, v52, s75, v92
	v_cndmask_b32_e64 v93, v204, v102, s[10:11]
	v_cndmask_b32_e64 v94, v204, v103, s[12:13]
	v_max3_f32 v54, v54, v93, v94
	v_cndmask_b32_e64 v95, v204, v88, s[14:15]
	v_cndmask_b32_e64 v100, v204, v89, s[16:17]
	v_max3_f32 v54, v54, v95, v100
	v_cndmask_b32_e64 v90, v204, v90, s[18:19]
	v_cndmask_b32_e64 v91, v204, v91, s[20:21]
	v_max3_f32 v54, v54, v90, v91
	v_mov_b32_e32 v88, v54
	s_nop 1
	v_permlane16_swap_b32_e32 v88, v54
	v_mov_b32_e32 v188, v53
	v_cvt_pk_bf16_f32 v48, v55, v165
	v_cvt_pk_bf16_f32 v49, v171, v173
	v_cvt_pk_bf16_f32 v50, v175, v177
	s_waitcnt lgkmcnt(0)
	v_max_f32_e32 v88, v88, v88
	v_max_f32_e32 v54, v54, v88
	v_mov_b32_e32 v88, v54
	s_nop 1
	v_permlane32_swap_b32_e32 v88, v54
	v_cvt_pk_bf16_f32 v51, v179, v181
	s_waitcnt lgkmcnt(0)
	v_max3_f32 v182, v195, v54, v88
	v_sub_f32_e32 v52, v52, v182
	v_exp_f32_e32 v54, v52
	v_sub_f32_e32 v52, v92, v182
	v_exp_f32_e32 v164, v52
	v_sub_f32_e32 v52, v93, v182
	v_exp_f32_e32 v170, v52
	v_sub_f32_e32 v52, v94, v182
	v_exp_f32_e32 v172, v52
	v_sub_f32_e32 v52, v95, v182
	v_pk_add_f32 v[88:89], v[54:55], 0 op_sel_hi:[1,0]
	v_exp_f32_e32 v174, v52
	v_sub_f32_e32 v52, v100, v182
	v_pk_add_f32 v[88:89], v[164:165], v[88:89]
	v_exp_f32_e32 v176, v52
	v_sub_f32_e32 v52, v90, v182
	v_pk_add_f32 v[88:89], v[170:171], v[88:89]
	v_exp_f32_e32 v178, v52
	v_sub_f32_e32 v52, v91, v182
	v_pk_add_f32 v[88:89], v[172:173], v[88:89]
	v_exp_f32_e32 v180, v52
	v_pk_add_f32 v[88:89], v[174:175], v[88:89]
	v_sub_f32_e32 v52, v195, v182
	v_pk_add_f32 v[88:89], v[176:177], v[88:89]
	v_exp_f32_e32 v52, v52
	v_pk_add_f32 v[88:89], v[178:179], v[88:89]
	v_pk_mul_f32 v[38:39], v[38:39], v[52:53] op_sel_hi:[1,0]
	v_pk_add_f32 v[88:89], v[180:181], v[88:89]
	v_mov_b32_e32 v91, v89
	s_nop 1
	v_permlane16_swap_b32_e32 v91, v89
	v_mov_b32_e32 v90, v88
	s_nop 1
	v_permlane16_swap_b32_e32 v90, v88
	v_pk_mul_f32 v[36:37], v[36:37], v[52:53] op_sel_hi:[1,0]
	v_pk_mul_f32 v[34:35], v[34:35], v[52:53] op_sel_hi:[1,0]
	v_pk_mul_f32 v[32:33], v[32:33], v[52:53] op_sel_hi:[1,0]
	v_pk_mul_f32 v[30:31], v[30:31], v[52:53] op_sel_hi:[1,0]
	s_waitcnt lgkmcnt(0)
	v_pk_add_f32 v[88:89], v[88:89], v[90:91]
	v_mov_b32_e32 v91, v89
	s_nop 1
	v_permlane32_swap_b32_e32 v91, v89
	v_mov_b32_e32 v90, v88
	s_nop 1
	v_permlane32_swap_b32_e32 v90, v88
	v_pk_mul_f32 v[28:29], v[28:29], v[52:53] op_sel_hi:[1,0]
	v_pk_mul_f32 v[26:27], v[26:27], v[52:53] op_sel_hi:[1,0]
	v_pk_mul_f32 v[24:25], v[24:25], v[52:53] op_sel_hi:[1,0]
	s_waitcnt lgkmcnt(0)
	v_pk_add_f32 v[132:133], v[88:89], v[90:91]
	v_pk_mul_f32 v[90:91], v[98:99], v[188:189] op_sel_hi:[1,0]
	v_pk_mul_f32 v[88:89], v[96:97], v[188:189] op_sel_hi:[1,0]
	v_pk_fma_f32 v[132:133], v[166:167], v[52:53], v[132:133]
	s_nop 0
	v_mfma_f32_16x16x32_bf16 v[100:103], v[68:71], v[48:51], v[88:91]
	s_nop 2
	v_mul_f32_e64 v90, v110, v188
	v_mul_f32_e64 v91, v111, v188
	v_pk_mul_f32 v[88:89], v[108:109], v[188:189] op_sel_hi:[1,0]
	s_nop 1
	v_mfma_f32_16x16x32_bf16 v[96:99], v[64:67], v[48:51], v[88:91]
	s_nop 2
	v_mul_f32_e64 v90, v114, v188
	v_mul_f32_e64 v91, v115, v188
	v_pk_mul_f32 v[88:89], v[112:113], v[188:189] op_sel_hi:[1,0]
	s_nop 1
	v_mfma_f32_16x16x32_bf16 v[92:95], v[60:63], v[48:51], v[88:91]
	s_nop 2
	v_mul_f32_e64 v90, v118, v188
	v_mul_f32_e64 v91, v119, v188
	v_pk_mul_f32 v[88:89], v[116:117], v[188:189] op_sel_hi:[1,0]
	s_nop 1
	v_mfma_f32_16x16x32_bf16 v[88:91], v[56:59], v[48:51], v[88:91]
	v_cvt_pk_bf16_f32 v48, v54, v164
	v_cvt_pk_bf16_f32 v49, v170, v172
	v_cvt_pk_bf16_f32 v50, v174, v176
	v_cvt_pk_bf16_f32 v51, v178, v180
	v_mfma_f32_16x16x32_bf16 v[52:55], v[128:131], v[120:123], 0
	v_mfma_f32_16x16x32_bf16 v[36:39], v[68:71], v[48:51], v[36:39]
	v_mfma_f32_16x16x32_bf16 v[32:35], v[64:67], v[48:51], v[32:35]
	v_mfma_f32_16x16x32_bf16 v[28:31], v[60:63], v[48:51], v[28:31]
	v_mfma_f32_16x16x32_bf16 v[24:27], v[56:59], v[48:51], v[24:27]
	v_mfma_f32_16x16x32_bf16 v[48:51], v[124:127], v[120:123], 0
	v_mfma_f32_16x16x32_bf16 v[48:51], v[44:47], v[104:107], v[48:51]
	v_mfma_f32_16x16x32_bf16 v[118:121], v[124:127], v[20:23], 0
	v_mfma_f32_16x16x32_bf16 v[52:55], v[84:87], v[104:107], v[52:55]
	s_nop 5
	v_cndmask_b32_e32 v48, v204, v48, vcc
	v_cndmask_b32_e64 v49, v204, v49, s[8:9]
	v_max3_f32 v104, v48, s75, v49
	v_mfma_f32_16x16x32_bf16 v[20:23], v[128:131], v[20:23], 0
	v_cndmask_b32_e64 v50, v204, v50, s[10:11]
	v_cndmask_b32_e64 v51, v204, v51, s[12:13]
	v_max3_f32 v104, v104, v50, v51
	v_mfma_f32_16x16x32_bf16 v[44:47], v[44:47], v[16:19], v[118:121]
	v_cndmask_b32_e64 v52, v204, v52, s[14:15]
	v_cndmask_b32_e64 v53, v204, v53, s[16:17]
	v_max3_f32 v104, v104, v52, v53
	v_cndmask_b32_e64 v54, v204, v54, s[18:19]
	v_cndmask_b32_e64 v106, v204, v55, s[20:21]
	v_mfma_f32_16x16x32_bf16 v[16:19], v[84:87], v[16:19], v[20:23]
	v_max3_f32 v55, v104, v54, v106
	v_mov_b32_e32 v104, v55
	s_nop 1
	v_permlane16_swap_b32_e32 v104, v55
	s_waitcnt lgkmcnt(0)
	v_max_f32_e32 v104, v104, v104
	v_cndmask_b32_e32 v20, v204, v44, vcc
	v_cndmask_b32_e64 v21, v204, v45, s[8:9]
	v_max3_f32 v22, v20, s75, v21
	v_cndmask_b32_e64 v23, v204, v46, s[10:11]
	v_cndmask_b32_e64 v44, v204, v47, s[12:13]
	v_max3_f32 v22, v22, v23, v44
	v_cndmask_b32_e64 v45, v204, v16, s[14:15]
	v_cndmask_b32_e64 v46, v204, v17, s[16:17]
	v_max3_f32 v16, v22, v45, v46
	v_cndmask_b32_e64 v18, v204, v18, s[18:19]
	v_cndmask_b32_e64 v19, v204, v19, s[20:21]
	v_max3_f32 v16, v16, v18, v19
	v_mov_b32_e32 v17, v16
	s_nop 1
	v_permlane16_swap_b32_e32 v17, v16
	v_max_f32_e32 v55, v55, v104
	v_mov_b32_e32 v104, v55
	s_nop 1
	v_permlane32_swap_b32_e32 v104, v55
	s_andn2_b64 vcc, exec, s[4:5]
	s_waitcnt lgkmcnt(0)
	v_max_f32_e32 v17, v17, v17
	v_max_f32_e32 v16, v16, v17
	s_waitcnt lgkmcnt(0)
	v_max3_f32 v170, v196, v55, v104
	v_mov_b32_e32 v17, v16
	s_nop 1
	v_permlane32_swap_b32_e32 v17, v16
	v_sub_f32_e32 v48, v48, v170
	v_exp_f32_e32 v55, v48
	v_sub_f32_e32 v48, v49, v170
	v_exp_f32_e32 v105, v48
	v_sub_f32_e32 v48, v50, v170
	v_exp_f32_e32 v107, v48
	v_sub_f32_e32 v48, v51, v170
	v_exp_f32_e32 v109, v48
	v_sub_f32_e32 v48, v52, v170
	s_waitcnt lgkmcnt(0)
	v_max3_f32 v188, v197, v16, v17
	v_exp_f32_e32 v111, v48
	v_sub_f32_e32 v48, v53, v170
	v_sub_f32_e32 v16, v20, v188
	v_sub_f32_e32 v104, v196, v170
	v_exp_f32_e32 v113, v48
	v_sub_f32_e32 v48, v54, v170
	v_exp_f32_e32 v54, v16
	v_sub_f32_e32 v20, v21, v188
	v_exp_f32_e32 v53, v104
	v_exp_f32_e32 v104, v20
	v_sub_f32_e32 v20, v23, v188
	v_exp_f32_e32 v115, v48
	v_sub_f32_e32 v48, v106, v170
	v_exp_f32_e32 v106, v20
	v_sub_f32_e32 v20, v44, v188
	v_exp_f32_e32 v108, v20
	v_sub_f32_e32 v20, v45, v188
	v_pk_add_f32 v[16:17], v[54:55], 0 op_sel_hi:[1,0]
	v_exp_f32_e32 v110, v20
	v_sub_f32_e32 v20, v46, v188
	v_pk_add_f32 v[16:17], v[104:105], v[16:17]
	v_exp_f32_e32 v112, v20
	v_sub_f32_e32 v18, v18, v188
	v_pk_add_f32 v[16:17], v[106:107], v[16:17]
	v_exp_f32_e32 v114, v18
	v_sub_f32_e32 v18, v19, v188
	v_exp_f32_e32 v117, v48
	v_pk_add_f32 v[16:17], v[108:109], v[16:17]
	v_exp_f32_e32 v116, v18
	v_pk_add_f32 v[16:17], v[110:111], v[16:17]
	v_mov_b32_e32 v86, v53
	v_pk_add_f32 v[16:17], v[112:113], v[16:17]
	v_cvt_pk_bf16_f32 v48, v55, v105
	v_cvt_pk_bf16_f32 v49, v107, v109
	v_cvt_pk_bf16_f32 v50, v111, v113
	v_cvt_pk_bf16_f32 v51, v115, v117
	s_nop 0
	v_pk_add_f32 v[16:17], v[114:115], v[16:17]
	s_nop 0
	v_pk_add_f32 v[16:17], v[116:117], v[16:17]
	v_mov_b32_e32 v19, v17
	s_nop 1
	v_permlane16_swap_b32_e32 v19, v17
	v_mov_b32_e32 v18, v16
	s_nop 1
	v_permlane16_swap_b32_e32 v18, v16
	s_waitcnt lgkmcnt(0)
	v_pk_add_f32 v[16:17], v[16:17], v[18:19]
	v_sub_f32_e32 v18, v197, v188
	v_mov_b32_e32 v19, v17
	s_nop 1
	v_permlane32_swap_b32_e32 v19, v17
	v_exp_f32_e32 v52, v18
	v_mov_b32_e32 v18, v16
	s_nop 1
	v_permlane32_swap_b32_e32 v18, v16
	v_pk_mul_f32 v[14:15], v[14:15], v[52:53] op_sel_hi:[1,0]
	v_pk_mul_f32 v[12:13], v[12:13], v[52:53] op_sel_hi:[1,0]
	s_waitcnt lgkmcnt(0)
	v_pk_add_f32 v[84:85], v[16:17], v[18:19]
	v_pk_mul_f32 v[18:19], v[42:43], v[86:87] op_sel_hi:[1,0]
	v_pk_mul_f32 v[16:17], v[40:41], v[86:87] op_sel_hi:[1,0]
	v_pk_mul_f32 v[10:11], v[10:11], v[52:53] op_sel_hi:[1,0]
	v_pk_mul_f32 v[8:9], v[8:9], v[52:53] op_sel_hi:[1,0]
	v_mfma_f32_16x16x32_bf16 v[44:47], v[68:71], v[48:51], v[16:19]
	v_mul_f32_e64 v6, v6, v52
	v_mul_f32_e64 v7, v7, v52
	v_pk_mul_f32 v[4:5], v[4:5], v[52:53] op_sel_hi:[1,0]
	v_pk_mul_f32 v[2:3], v[2:3], v[52:53] op_sel_hi:[1,0]
	v_pk_mul_f32 v[18:19], v[74:75], v[86:87] op_sel_hi:[1,0]
	v_pk_mul_f32 v[16:17], v[72:73], v[86:87] op_sel_hi:[1,0]
	v_pk_mul_f32 v[0:1], v[0:1], v[52:53] op_sel_hi:[1,0]
	v_pk_fma_f32 v[164:165], v[134:135], v[52:53], v[84:85]
	v_mfma_f32_16x16x32_bf16 v[40:43], v[64:67], v[48:51], v[16:19]
	s_nop 2
	v_mul_f32_e64 v18, v78, v86
	v_mul_f32_e64 v19, v79, v86
	v_pk_mul_f32 v[16:17], v[76:77], v[86:87] op_sel_hi:[1,0]
	s_nop 1
	v_mfma_f32_16x16x32_bf16 v[20:23], v[60:63], v[48:51], v[16:19]
	s_nop 2
	v_mul_f32_e64 v18, v82, v86
	v_mul_f32_e64 v19, v83, v86
	v_pk_mul_f32 v[16:17], v[80:81], v[86:87] op_sel_hi:[1,0]
	s_nop 1
	v_mfma_f32_16x16x32_bf16 v[16:19], v[56:59], v[48:51], v[16:19]
	v_cvt_pk_bf16_f32 v48, v54, v104
	v_cvt_pk_bf16_f32 v49, v106, v108
	v_cvt_pk_bf16_f32 v50, v110, v112
	v_cvt_pk_bf16_f32 v51, v114, v116
	s_nop 0
	v_mfma_f32_16x16x32_bf16 v[12:15], v[68:71], v[48:51], v[12:15]
	v_mfma_f32_16x16x32_bf16 v[8:11], v[64:67], v[48:51], v[8:11]
	v_mfma_f32_16x16x32_bf16 v[4:7], v[60:63], v[48:51], v[4:7]
	v_mfma_f32_16x16x32_bf16 v[0:3], v[56:59], v[48:51], v[0:3]
	v_cndmask_b32_e64 v48, 0, 1, s[6:7]
	s_nop 0
	v_readfirstlane_b32 s6, v48
	s_xor_b32 s84, s84, s6
	s_cbranch_vccz .LBB0_69
